# GU gate/up GEMM with 288-row tiles (1408 units, A' extra rows folded, saddr DMA loop), GU early-rstd dropped, conversions on WGs 48-175
# baseline (speedup 1.0000x reference)
; #define LAS __attribute__((address_space(3)))
; #define LAS __attribute__((address_space(3)))
; __global__ void __launch_bounds__(NWAVES * 64, 2) hymba_fwd(Args args) {
;     ...
;             const int l = (ph - 1) / 5, sub = (ph - 1) % 5;
;             if (sub == 0) {
;                 if ((PHMASK & 2) && l == 0) {
;                     pg8::Gemm gm{(const pg8::bf16_t*)(ws + WS_MEMB), (const pg8::bf16_t*)(ws + WS_WMEM), NBP * NMEM, DEPTH * 512, D};
;                     pg8::StaticOrder S; S.init(NBP * NMEM, DEPTH * 512, G, (int)blockIdx.x);
;                     pg8::EpiMem E{ws, args.out};
;                     pg8::gemm_phase<pg8::EpiMem, pg8::StaticOrder, true, true>(lds, gm, S, E);
;                 }
;                 pg8::Gemm gm{(const pg8::bf16_t*)(ws + WS_AB), (const pg8::bf16_t*)(ws + WS_WIN) + (size_t)l * INW * D, MT, INW, D};
;                 pg8::StaticOrder S; S.init(MT, INW, G, (int)blockIdx.x);
;                 pg8::EpiIn E{ws, args.out, lds, l, 0};
;                 if (PHMASK & 4) pg8::gemm_phase<pg8::EpiIn, pg8::StaticOrder, true, true>(lds, gm, S, E);
;                 if (l == 0 && blockIdx.x >= 64) {
;     ...
;             } else if (sub == 3) {
;                 pg8::Gemm gm{(const pg8::bf16_t*)(ws + WS_AB), (const pg8::bf16_t*)(ws + WS_WGU) + (size_t)l * 2 * DFF * D, MT, 2 * DFF, D};
;                 pg8::StaticOrder S; S.init(MT, 2 * DFF, G, (int)blockIdx.x);
;                 pg8::EpiGU E{ws, lds};
;                 if (PHMASK & 32) pg8::gemm_phase<pg8::EpiGU, pg8::StaticOrder, true, true>(lds, gm, S, E);
;                 if (l + 1 < DEPTH && blockIdx.x >= 48) {
;                     int ln = lane, tn = tid; asm volatile("" : "+v"(ln), "+v"(tn));
;                     const int wk = ((int)blockIdx.x - 48) * NWAVES + wave, nwk = (G - 48) * NWAVES;
;                     convert_layer_weights(args, ws, (LAS float*)(lds + wave * 16384), l + 1, wk, nwk, ln, 12);
;                     convert_layer_caches(args, ws, (LAS float*)(lds + wave * 16384), l + 1, wk, nwk, ((int)blockIdx.x - 48) * (NWAVES * 64) + tn, (G - 48) * NWAVES * 64, ln);
;                 }
.LBB0_18:
	s_add_u32 s4, s0, 0xd0
	s_addc_u32 s5, s1, 0
	v_writelane_b32 v251, s4, 3
	s_load_dwordx16 s[16:31], s[0:1], 0x40
	s_load_dwordx16 s[60:75], s[0:1], 0x80
	v_writelane_b32 v251, s5, 4
	s_lshr_b32 s4, s13, 6
	v_readlane_b32 s42, v251, 0
	s_load_dword s58, s[0:1], 0xd0
	s_cmpk_lt_i32 s42, 0x630
	s_cselect_b64 s[6:7], -1, 0
	s_ashr_i32 s59, s42, 31
	v_writelane_b32 v251, s6, 5
	s_lshr_b32 s5, s59, 29
	s_load_dwordx16 s[76:91], s[0:1], 0x0
	v_writelane_b32 v251, s7, 6
	s_add_i32 s6, s42, s5
	s_ashr_i32 s5, s6, 3
	s_and_b32 s6, s6, -8
	s_sub_i32 s8, s42, s6
	s_waitcnt lgkmcnt(0)
	s_ashr_i32 s6, s58, 31
	s_cmp_gt_u32 s42, 47
	v_writelane_b32 v251, s6, 7
	s_cselect_b64 s[6:7], -1, 0
	s_lshl_b32 s9, s42, 3
	s_add_i32 s33, s4, s9
	s_lshl_b32 s92, s58, 3
	s_lshl_b32 s9, s4, 14
	s_add_i32 s34, s33, 0xfffffe80
	s_movk_i32 s10, 0x400
	s_add_i32 s9, s9, 0
	s_cmpk_lt_i32 s34, 0x1080
	v_writelane_b32 v251, s9, 8
	s_cselect_b64 s[14:15], -1, 0
	v_writelane_b32 v251, s14, 9
	s_cmp_lg_u64 s[68:69], 0
	v_mbcnt_lo_u32_b32 v0, -1, 0
	v_writelane_b32 v251, s15, 10
	s_cselect_b64 s[14:15], -1, 0
	v_writelane_b32 v251, s14, 11
	s_cmp_lg_u64 s[16:17], 0
	s_cselect_b64 s[94:95], -1, 0
	v_writelane_b32 v251, s15, 12
	s_lshl_b32 s14, s42, 9
	s_add_i32 s9, s14, 0xffffa000
	s_lshl_b32 s36, s10, 6
	v_writelane_b32 v251, s9, 13
	s_cmpk_lt_i32 s34, 0x500
	v_writelane_b32 v251, s10, 14
	s_cselect_b64 s[10:11], -1, 0
	s_add_u32 s56, s74, 0x4000000
	s_addc_u32 s57, s75, 0
	v_writelane_b32 v251, s10, 15
	s_cmpk_lt_i32 s42, 0x100
	v_mov_b32_e32 v185, 0
	v_writelane_b32 v251, s11, 16
	s_cselect_b64 s[10:11], -1, 0
	s_lshl_b32 s9, s8, 5
	v_writelane_b32 v251, s10, 17
	s_cmpk_lt_i32 s42, 0x140
	v_mov_b32_e32 v218, 0x358637bd
	v_writelane_b32 v251, s11, 18
	s_cselect_b64 s[10:11], -1, 0
	v_writelane_b32 v251, s10, 19
	s_and_b32 s38, s13, 0xffffff00
	v_mov_b32_e32 v219, 0x260
	v_writelane_b32 v251, s11, 20
	s_lshr_b32 s10, s13, 2
	s_and_b32 s15, s10, 48
	s_lshr_b32 s10, s13, 8
	s_mul_i32 s11, s10, 0x9000
	s_add_i32 s35, s11, 0
	v_writelane_b32 v251, s15, 21
	s_lshl_b32 s11, s15, 2
	s_lshl_b32 s15, s10, 6
	v_writelane_b32 v251, s15, 22
	s_mulk_i32 s10, 0xdc00
	s_add_i32 s11, s11, 0
	v_writelane_b32 v251, s35, 23
	s_add_i32 s10, s35, s10
	v_writelane_b32 v251, s10, 24
	s_add_i32 s10, s11, 0x22a00
	v_writelane_b32 v251, s10, 25
	s_add_i32 s10, s10, s38
	v_writelane_b32 v251, s10, 26
	s_and_b32 s10, s4, 0x3fffffc
	s_add_i32 s11, s11, 0x22800
	v_writelane_b32 v251, s10, 27
	s_lshl_b32 s10, s10, 6
	v_writelane_b32 v251, s10, 28
	s_add_i32 s10, s11, s38
	v_writelane_b32 v251, s11, 29
	s_cmp_gt_u32 s42, 63
	v_writelane_b32 v251, s10, 30
	s_cselect_b64 s[10:11], -1, 0
	v_writelane_b32 v251, s10, 31
	s_add_i32 s35, s33, 0xfffffe00
	v_mov_b32_e32 v221, 1
	v_writelane_b32 v251, s11, 32
	s_add_i32 s10, s92, 0xfffffe00
	s_cmpk_lt_i32 s35, 0x580
	s_cselect_b64 s[40:41], -1, 0
	v_writelane_b32 v251, s40, 33
	s_cmp_lg_u64 s[64:65], 0
	v_mov_b64_e32 v[186:187], 0x100
	v_writelane_b32 v251, s41, 34
	s_cselect_b64 s[40:41], -1, 0
	v_writelane_b32 v251, s40, 35
	s_add_i32 s11, s14, 0xffff8000
	v_mov_b64_e32 v[188:189], 0xff
	v_writelane_b32 v251, s41, 36
	v_writelane_b32 v251, s14, 37
	v_writelane_b32 v251, s11, 38
	v_writelane_b32 v251, s10, 39
	s_lshl_b32 s10, s10, 6
	s_cmp_lt_i32 s42, 64
	v_writelane_b32 v251, s10, 40
	s_cselect_b64 s[10:11], -1, 0
	v_writelane_b32 v251, s10, 41
	v_mbcnt_hi_u32_b32 v222, -1, v0
	v_mov_b64_e32 v[192:193], 0x1f7
	v_writelane_b32 v251, s11, 42
	s_lshl_b32 s10, s8, 3
	s_add_u32 s11, s74, 0x5410000
	v_writelane_b32 v251, s11, 43
	s_addc_u32 s11, s75, 0
	v_writelane_b32 v251, s11, 44
	s_add_u32 s11, s74, 0x4c10000
	v_writelane_b32 v251, s11, 45
	s_addc_u32 s11, s75, 0
	s_cmpk_lt_i32 s42, 0x1f8
	v_writelane_b32 v251, s11, 46
	s_cselect_b64 s[14:15], -1, 0
	v_writelane_b32 v251, s14, 47
	s_lshl_b32 s11, s8, 6
	s_add_u32 s13, s74, 0x4c00000
	v_writelane_b32 v251, s15, 48
	v_writelane_b32 v251, s13, 49
	s_addc_u32 s13, s75, 0
	v_writelane_b32 v251, s13, 50
	s_add_u32 s13, s74, 0x6c10000
	v_writelane_b32 v251, s13, 51
	s_addc_u32 s13, s75, 0
	v_writelane_b32 v251, s13, 52
	s_add_u32 s13, s74, 0x4a00000
	v_writelane_b32 v251, s13, 53
	s_addc_u32 s13, s75, 0
	v_writelane_b32 v251, s13, 54
	s_add_u32 s13, s74, 0x6410000
	v_writelane_b32 v251, s13, 55
	s_addc_u32 s13, s75, 0
	v_writelane_b32 v251, s13, 56
	s_add_u32 s13, s74, 0x4800000
	v_writelane_b32 v251, s13, 57
	s_addc_u32 s13, s75, 0
	v_writelane_b32 v251, s13, 58
	s_add_u32 s13, s74, 0x5c10000
	v_writelane_b32 v251, s13, 59
	s_addc_u32 s13, s75, 0
	s_cmpk_lt_i32 s35, 0x1280
	v_writelane_b32 v251, s13, 60
	s_cselect_b64 s[14:15], -1, 0
	v_writelane_b32 v251, s14, 61
	s_cmpk_lt_i32 s33, 0x380
	s_mov_b64 s[96:97], 0x80
	v_writelane_b32 v251, s15, 62
	s_cselect_b64 s[14:15], -1, 0
	v_writelane_b32 v251, s14, 63
	s_cmpk_lt_i32 s33, 0x400
	s_nop 0
	v_writelane_b32 v252, s15, 0
	s_cselect_b64 s[14:15], -1, 0
	v_writelane_b32 v252, s14, 1
	s_nop 1
	v_writelane_b32 v252, s15, 2
	v_writelane_b32 v252, s16, 3
	s_cmp_lg_u64 s[28:29], 0
	s_cselect_b64 s[14:15], -1, 0
	v_writelane_b32 v252, s17, 4
	v_writelane_b32 v252, s18, 5
	v_writelane_b32 v252, s19, 6
	v_writelane_b32 v252, s20, 7
	v_writelane_b32 v252, s21, 8
	v_writelane_b32 v252, s22, 9
	v_writelane_b32 v252, s23, 10
	v_writelane_b32 v252, s24, 11
	v_writelane_b32 v252, s25, 12
	v_writelane_b32 v252, s26, 13
	v_writelane_b32 v252, s27, 14
	v_writelane_b32 v252, s28, 15
	v_writelane_b32 v252, s29, 16
	v_writelane_b32 v252, s30, 17
	v_writelane_b32 v252, s31, 18
	s_lshl_b32 s20, s58, 9
	v_writelane_b32 v252, s14, 19
	s_cmpk_lt_i32 s33, 0x500
	s_movk_i32 s29, 0x5800
; #define LAS __attribute__((address_space(3)))
; #define LAS __attribute__((address_space(3)))
;     __host__ __device__ bool next(int i, Unit& u) const {
;         const long L = (long)i * G + c; if (L >= nwg) return false;
;         int wgid = (int)L; { const int q = nwg / NXCD, r = nwg % NXCD, xcd = wgid % NXCD, off = wgid / NXCD; wgid = (xcd < r ? xcd * (q + 1) : r * (q + 1) + (xcd - r) * q) + off; }
;         const int nig = WGM * nN, gid = wgid / nig, fm = gid * WGM, gsz = (nM - fm) < WGM ? (nM - fm) : WGM;
;         u.pm = fm + ((wgid % nig) % gsz); u.pn = (wgid % nig) / gsz; return true;
;     }
; __device__ __forceinline__ unsigned xb_ld(unsigned* p)              { return __hip_atomic_load(p, __ATOMIC_RELAXED, __HIP_MEMORY_SCOPE_AGENT); }
; __device__ __forceinline__ unsigned xb_add(unsigned* p, unsigned v) { return __hip_atomic_fetch_add(p, v, __ATOMIC_RELAXED, __HIP_MEMORY_SCOPE_AGENT); }
; __device__ __forceinline__ unsigned xb_xcc_id() { return (unsigned)__builtin_amdgcn_s_getreg((3 << 11) | 20) & 0xFu; }
; __device__ __forceinline__ XcdBarrier xcd_barrier_post(unsigned* bar, volatile LAS unsigned* st) {
;     XcdBarrier b; b.bar = bar; b.x = xb_xcc_id(); b.st = st;
;     if (threadIdx.x == 0) (void)xb_add(&bar[XB_XCNT(b.x)], 1u);
;     return b;
; }
; __device__ __forceinline__ void xcd_barrier_complete(unsigned* bar, unsigned x, unsigned& nloc, unsigned& nx) {
;     const unsigned G = gridDim.x * gridDim.y * gridDim.z;
;     unsigned sum, cnt, mine, sp = 0u;
;     for (;;) {
;         sum = 0u; cnt = 0u; mine = 0u;
; #pragma unroll
;         for (unsigned j = 0; j < 16; ++j) { const unsigned c = xb_ld(&bar[XB_XCNT(j)]); sum += c; cnt += (c > 0u) ? 1u : 0u; mine = (j == x) ? c : mine; }
;         if (sum == G) break;
;         __builtin_amdgcn_s_sleep(1);
;         if ((++sp & 255u) == 0u) { if (xb_ld(&bar[XB_TMO])) break; if (sp > XB_SPIN_CAP) { atomicAdd(&bar[XB_TMO], 1u); break; } }
;     }
;     nloc = mine > 0u ? mine : 1u; nx = cnt > 0u ? cnt : 1u;
; }
	v_writelane_b32 v252, s15, 20
	s_cselect_b64 s[14:15], -1, 0
	v_writelane_b32 v252, s14, 21
	s_cmpk_lt_i32 s33, 0x2800
	s_nop 0
	v_writelane_b32 v252, s15, 22
	s_cselect_b64 s[14:15], -1, 0
	s_lshl_b32 s22, s33, 1
	v_writelane_b32 v252, s14, 23
	s_cmp_eq_u32 s42, 0
	s_nop 0
	v_writelane_b32 v252, s15, 24
	s_cselect_b64 s[14:15], -1, 0
	v_writelane_b32 v252, s14, 25
	s_nop 1
	v_writelane_b32 v252, s15, 26
	s_add_u32 s14, s52, 0x4200
	s_addc_u32 s15, s53, 0
	v_writelane_b32 v252, s14, 27
	s_nop 1
	v_writelane_b32 v252, s15, 28
	s_add_u32 s14, s52, 0x4400
	s_addc_u32 s15, s53, 0
	v_writelane_b32 v252, s14, 29
	s_nop 1
	v_writelane_b32 v252, s15, 30
	s_add_u32 s14, s52, 0x4500
	s_addc_u32 s15, s53, 0
	v_writelane_b32 v252, s14, 31
	s_nop 1
	v_writelane_b32 v252, s15, 32
	s_add_u32 s14, s52, 0x4600
	s_addc_u32 s15, s53, 0
	v_writelane_b32 v252, s14, 33
	s_nop 1
	v_writelane_b32 v252, s15, 34
	s_add_u32 s14, s52, 0x4700
	s_addc_u32 s15, s53, 0
	v_writelane_b32 v252, s14, 35
	s_nop 1
	v_writelane_b32 v252, s15, 36
	s_add_u32 s14, s52, 0x4800
	s_addc_u32 s15, s53, 0
	v_writelane_b32 v252, s14, 37
	s_nop 1
	v_writelane_b32 v252, s15, 38
	s_add_u32 s14, s52, 0x4900
	s_addc_u32 s15, s53, 0
	v_writelane_b32 v252, s14, 39
	s_nop 1
	v_writelane_b32 v252, s15, 40
	s_add_u32 s14, s52, 0x4a00
	s_addc_u32 s15, s53, 0
	v_writelane_b32 v252, s14, 41
	s_nop 1
	v_writelane_b32 v252, s15, 42
	s_add_u32 s14, s52, 0x4b00
	s_addc_u32 s15, s53, 0
	v_writelane_b32 v252, s14, 43
	s_nop 1
	v_writelane_b32 v252, s15, 44
	s_add_u32 s14, s52, 0x4c00
	s_addc_u32 s15, s53, 0
	v_writelane_b32 v252, s14, 45
	s_nop 1
	v_writelane_b32 v252, s15, 46
	s_add_u32 s14, s52, 0x4d00
	s_addc_u32 s15, s53, 0
	v_writelane_b32 v252, s14, 47
	s_nop 1
	v_writelane_b32 v252, s15, 48
	s_add_u32 s14, s52, 0x4e00
	s_addc_u32 s15, s53, 0
	v_writelane_b32 v252, s14, 49
	s_nop 1
	v_writelane_b32 v252, s15, 50
	s_add_u32 s14, s52, 0x4f00
	s_addc_u32 s15, s53, 0
	v_writelane_b32 v252, s14, 51
	s_nop 1
	v_writelane_b32 v252, s15, 52
	s_add_u32 s14, s52, 0x5000
	s_addc_u32 s15, s53, 0
	v_writelane_b32 v252, s14, 53
	s_nop 1
	v_writelane_b32 v252, s15, 54
	s_add_u32 s14, s52, 0x5100
	s_addc_u32 s15, s53, 0
	v_writelane_b32 v252, s14, 55
	s_nop 1
	v_writelane_b32 v252, s15, 56
	s_add_u32 s14, s52, 0x5200
	s_addc_u32 s15, s53, 0
	v_writelane_b32 v252, s14, 57
	s_nop 1
	v_writelane_b32 v252, s15, 58
	s_add_u32 s14, s52, 0x5300
	s_addc_u32 s15, s53, 0
	v_writelane_b32 v252, s14, 59
	s_cmp_eq_u32 s12, 15
	s_nop 0
	v_writelane_b32 v252, s15, 60
	s_cselect_b64 s[14:15], -1, 0
	v_writelane_b32 v252, s14, 61
	s_cmp_eq_u32 s12, 14
	s_nop 0
	v_writelane_b32 v252, s15, 62
	s_cselect_b64 s[14:15], -1, 0
	v_writelane_b32 v252, s14, 63
	s_cmp_eq_u32 s12, 13
	s_nop 0
	v_writelane_b32 v253, s15, 0
	s_cselect_b64 s[14:15], -1, 0
	v_writelane_b32 v253, s14, 1
	s_cmp_eq_u32 s12, 12
	s_nop 0
	v_writelane_b32 v253, s15, 2
	s_cselect_b64 s[14:15], -1, 0
	v_writelane_b32 v253, s14, 3
	s_cmp_eq_u32 s12, 11
	s_nop 0
	v_writelane_b32 v253, s15, 4
	s_cselect_b64 s[14:15], -1, 0
	v_writelane_b32 v253, s14, 5
	s_cmp_eq_u32 s12, 10
	s_nop 0
	v_writelane_b32 v253, s15, 6
	s_cselect_b64 s[14:15], -1, 0
	v_writelane_b32 v253, s14, 7
	s_cmp_eq_u32 s12, 9
	s_nop 0
	v_writelane_b32 v253, s15, 8
	s_cselect_b64 s[14:15], -1, 0
	v_writelane_b32 v253, s14, 9
	s_cmp_eq_u32 s12, 8
	s_nop 0
	v_writelane_b32 v253, s15, 10
	s_cselect_b64 s[14:15], -1, 0
	v_writelane_b32 v253, s14, 11
	s_cmp_eq_u32 s12, 7
	s_nop 0
	v_writelane_b32 v253, s15, 12
	s_cselect_b64 s[14:15], -1, 0
	v_writelane_b32 v253, s14, 13
	s_cmp_eq_u32 s12, 6
	s_nop 0
	v_writelane_b32 v253, s15, 14
	s_cselect_b64 s[14:15], -1, 0
	v_writelane_b32 v253, s14, 15
	s_cmp_eq_u32 s12, 5
	s_nop 0
	v_writelane_b32 v253, s15, 16
	s_cselect_b64 s[14:15], -1, 0
	v_writelane_b32 v253, s14, 17
	s_cmp_eq_u32 s12, 4
	s_nop 0
	v_writelane_b32 v253, s15, 18
	s_cselect_b64 s[14:15], -1, 0
	v_writelane_b32 v253, s14, 19
	s_cmp_eq_u32 s12, 3
	s_nop 0
	v_writelane_b32 v253, s15, 20
	s_cselect_b64 s[14:15], -1, 0
	v_writelane_b32 v253, s14, 21
	s_cmp_eq_u32 s12, 2
	s_nop 0
	v_writelane_b32 v253, s15, 22
	s_cselect_b64 s[14:15], -1, 0
	v_writelane_b32 v253, s14, 23
	s_cmp_eq_u32 s12, 1
	s_nop 0
	v_writelane_b32 v253, s15, 24
	s_cselect_b64 s[14:15], -1, 0
	v_writelane_b32 v253, s14, 25
	s_cmp_eq_u32 s12, 0
	s_nop 0
	v_writelane_b32 v253, s15, 26
	s_cselect_b64 s[14:15], -1, 0
	s_lshl_b32 s12, s12, 8
	s_add_u32 s2, s2, s12
	s_addc_u32 s3, s3, 0
	v_writelane_b32 v253, s14, 27
	s_add_u32 s12, s2, 0x1400
	s_addc_u32 s13, s3, 0
	v_writelane_b32 v253, s15, 28
	v_writelane_b32 v253, s12, 29
	s_add_u32 s2, s2, 0x2400
	s_addc_u32 s3, s3, 0
	v_writelane_b32 v253, s13, 30
	v_writelane_b32 v253, s2, 31
	s_nop 1
	v_writelane_b32 v253, s3, 32
	s_add_u32 s2, s52, 0x7400
	s_addc_u32 s3, s53, 0
	v_writelane_b32 v253, s2, 33
	s_nop 1
	v_writelane_b32 v253, s3, 34
	s_add_u32 s2, s52, 0x7500
	s_addc_u32 s3, s53, 0
	v_writelane_b32 v253, s2, 35
	s_cmp_lt_i32 s8, 0
	s_nop 0
	v_writelane_b32 v253, s3, 36
	s_mul_i32 s2, s8, 33
	s_cselect_b32 s2, s2, s9
	s_movk_i32 s9, 0xc7
	s_cselect_b32 s9, s9, 0xc6
	s_mul_i32 s3, s8, 9
	s_mul_i32 s9, s8, s9
	s_mul_i32 s8, s8, 63
	s_cselect_b32 s3, s3, s10
	s_cselect_b32 s8, s11, s8
	s_add_i32 s9, s9, s5
	s_mul_hi_i32 s10, s9, 0x2e8ba2e9
	s_lshr_b32 s11, s10, 31
	s_ashr_i32 s10, s10, 5
	s_add_i32 s10, s10, s11
	s_mul_i32 s11, s10, 0xb0
	s_sub_i32 s9, s9, s11
	s_bfe_u32 s11, s9, 0x3001c
	s_add_i32 s11, s9, s11
	s_and_b32 s12, s11, 0xfff8
	s_add_i32 s2, s2, s5
	s_sub_i32 s9, s9, s12
	s_ashr_i32 s12, s2, 31
	s_lshr_b32 s12, s12, 27
	s_add_i32 s12, s2, s12
	s_and_b32 s13, s12, 0xffe0
; #define LAS __attribute__((address_space(3)))
; #define LAS __attribute__((address_space(3)))
;     __host__ __device__ bool next(int i, Unit& u) const {
;         const long L = (long)i * G + c; if (L >= nwg) return false;
;         int wgid = (int)L; { const int q = nwg / NXCD, r = nwg % NXCD, xcd = wgid % NXCD, off = wgid / NXCD; wgid = (xcd < r ? xcd * (q + 1) : r * (q + 1) + (xcd - r) * q) + off; }
;         const int nig = WGM * nN, gid = wgid / nig, fm = gid * WGM, gsz = (nM - fm) < WGM ? (nM - fm) : WGM;
;         u.pm = fm + ((wgid % nig) % gsz); u.pn = (wgid % nig) / gsz; return true;
; __global__ void __launch_bounds__(NWAVES * 64, 2) hymba_fwd(Args args) {
;     ...
;                     const int wk = ((int)blockIdx.x - 48) * NWAVES + wave, nwk = (G - 48) * NWAVES;
;                     convert_layer_weights(args, ws, (LAS float*)(lds + wave * 16384), l + 1, wk, nwk, ln, 12);
;                     convert_layer_caches(args, ws, (LAS float*)(lds + wave * 16384), l + 1, wk, nwk, ((int)blockIdx.x - 48) * (NWAVES * 64) + tn, (G - 48) * NWAVES * 64, ln);
	s_sub_i32 s2, s2, s13
	s_bfe_i32 s13, s2, 0x80000
	s_bfe_u32 s13, s13, 0x3000c
	s_add_i32 s13, s2, s13
	s_and_b32 s14, s13, 0xf8
	s_sub_i32 s14, s2, s14
	s_add_i32 s2, s3, s5
	s_ashr_i32 s3, s2, 31
	s_lshr_b32 s3, s3, 26
	s_add_i32 s15, s2, s3
	s_and_b32 s3, s15, 0xffc0
	s_sub_i32 s2, s2, s3
	s_bfe_i32 s3, s2, 0x80000
	s_bfe_u32 s3, s3, 0x3000c
	s_add_i32 s16, s2, s3
	s_and_b32 s3, s16, 0xf8
	s_add_i32 s8, s8, s5
	s_sub_i32 s17, s2, s3
	s_mul_hi_i32 s2, s8, 0x92492493
	s_add_i32 s2, s2, s8
	s_lshr_b32 s3, s2, 31
	s_ashr_i32 s2, s2, 5
	s_add_i32 s5, s2, s3
	s_mul_i32 s2, s5, 56
	s_sub_i32 s2, s8, s2
	s_bfe_i32 s3, s2, 0x80000
	s_bfe_u32 s3, s3, 0x3000c
	s_add_i32 s8, s2, s3
	s_and_b32 s3, s8, 0xf8
	s_sub_i32 s18, s2, s3
	s_lshl_b32 s2, s42, 4
	s_lshl_b32 s3, s4, 1
	s_add_i32 s19, s2, s3
	s_lshl_b32 s2, s10, 3
	s_sext_i32_i16 s3, s11
	s_sext_i32_i16 s9, s9
	s_add_i32 s24, s2, s9
	s_ashr_i32 s2, s3, 3
	v_writelane_b32 v253, s2, 37
	s_lshr_b32 s2, s3, 3
	s_bfe_i64 s[2:3], s[2:3], 0x100000
	s_lshl_b64 s[2:3], s[2:3], 19
	v_writelane_b32 v253, s2, 38
	s_sext_i32_i8 s10, s17
	s_ashr_i32 s39, s38, 31
	v_writelane_b32 v253, s3, 39
	s_ashr_i32 s2, s12, 5
	s_bfe_i32 s3, s13, 0x80000
	s_lshl_b32 s2, s2, 3
	s_sext_i32_i16 s9, s3
	s_sext_i32_i8 s3, s14
	s_add_i32 s12, s2, s3
	s_ashr_i32 s2, s15, 6
	s_bfe_i32 s3, s16, 0x80000
	s_lshl_b32 s2, s2, 3
	s_sext_i32_i16 s3, s3
	s_add_i32 s10, s2, s10
	s_ashr_i32 s2, s3, 3
	v_writelane_b32 v253, s2, 40
	s_lshr_b32 s2, s3, 3
	s_bfe_i64 s[2:3], s[2:3], 0x100000
	s_lshl_b64 s[2:3], s[2:3], 19
	v_writelane_b32 v253, s2, 41
	s_lshl_b32 s93, s58, 8
	s_lshl_b32 s14, s58, 4
	v_writelane_b32 v253, s3, 42
	s_bfe_i32 s3, s8, 0x80000
	s_lshl_b32 s2, s5, 3
	s_sext_i32_i16 s5, s3
	s_sext_i32_i8 s3, s18
	s_add_i32 s8, s2, s3
	s_ashr_i32 s2, s9, 3
	v_writelane_b32 v253, s2, 43
	s_lshr_b32 s2, s9, 3
	s_bfe_i64 s[2:3], s[2:3], 0x100000
	s_lshl_b64 s[2:3], s[2:3], 19
	v_writelane_b32 v253, s2, 44
	s_ashr_i32 s25, s24, 31
	s_lshl_b64 s[16:17], s[24:25], 19
	v_writelane_b32 v253, s3, 45
	s_ashr_i32 s2, s5, 3
	v_writelane_b32 v253, s2, 46
	s_lshr_b32 s2, s5, 3
	s_bfe_i64 s[2:3], s[2:3], 0x100000
	s_lshl_b64 s[2:3], s[2:3], 19
	v_writelane_b32 v253, s2, 47
	s_ashr_i32 s11, s10, 31
	s_ashr_i32 s13, s12, 31
	v_writelane_b32 v253, s3, 48
	v_writelane_b32 v253, s38, 49
	s_lshl_b32 s2, s34, 5
	s_lshl_b32 s3, s58, 12
	v_writelane_b32 v253, s39, 50
	v_writelane_b32 v253, s34, 51
	v_writelane_b32 v253, s2, 52
	s_add_i32 s2, s93, 0xffffd000
	v_writelane_b32 v253, s2, 53
	s_add_i32 s2, s19, 0x7fffe700
	v_writelane_b32 v253, s2, 54
	s_add_i32 s2, s14, 0xfffffd00
	v_writelane_b32 v253, s2, 55
	s_sub_i32 s2, 0x180, s33
	v_writelane_b32 v253, s2, 56
	s_sub_i32 s2, 0x180, s92
	v_writelane_b32 v253, s2, 57
	s_lshl_b32 s2, s42, 12
	v_writelane_b32 v253, s2, 58
	s_add_i32 s2, s2, 0xfff50000
	v_writelane_b32 v253, s2, 59
	s_mov_b32 s2, 0x80000
	v_writelane_b32 v253, s2, 60
	s_mov_b32 s2, s24
	v_writelane_b32 v253, s2, 61
	s_ashr_i32 s9, s8, 31
	s_nop 0
	v_writelane_b32 v253, s3, 62
	v_writelane_b32 v253, s16, 63
	s_mov_b32 s2, s10
	s_lshl_b64 s[10:11], s[10:11], 19
	v_writelane_b32 v254, s17, 0
	v_writelane_b32 v254, s2, 1
	s_nop 1
	v_writelane_b32 v254, s3, 2
	v_writelane_b32 v254, s10, 3
	s_mov_b32 s2, s12
	s_nop 0
	v_writelane_b32 v254, s11, 4
	v_writelane_b32 v254, s2, 5
	s_lshl_b64 s[10:11], s[12:13], 19
	s_nop 0
	v_writelane_b32 v254, s3, 6
	v_writelane_b32 v254, s10, 7
	s_mov_b32 s2, s8
	s_lshl_b64 s[8:9], s[8:9], 19
	v_writelane_b32 v254, s11, 8
	v_writelane_b32 v254, s2, 9
	s_add_u32 s0, s82, 0x200000
	s_nop 0
	v_writelane_b32 v254, s3, 10
	v_writelane_b32 v254, s8, 11
	s_nop 1
; __global__ void __launch_bounds__(NWAVES * 64, 2) hymba_fwd(Args args) {
;     ...
;     const int G = gridDim.x;
;     for (int ph = lo; ph < hi; ++ph) {
;         size_t zoff = 0; asm volatile("" : "+s"(zoff));
;         unsigned char* ws = args.ws + zoff;
;         if (ph == 0) {
;             if (PHMASK & 1) p0_prologue(args, ws, lds, tid, lane, wave);
;     ...
;             __syncthreads(); p0_prologue(args, ws, lds, tid, lane, wave);
;     ...
;         } else {
;             const int l = (ph - 1) / 5, sub = (ph - 1) % 5;
	v_writelane_b32 v254, s9, 12
	v_writelane_b32 v254, s0, 13
	s_addc_u32 s0, s83, 0
	s_ashr_i32 s37, s36, 31
	v_writelane_b32 v254, s0, 14
	s_lshl_b64 s[0:1], s[36:37], 5
	v_writelane_b32 v254, s0, 15
	s_nop 1
	v_writelane_b32 v254, s1, 16
	s_add_u32 s0, s52, 0xb100000
	v_writelane_b32 v254, s0, 17
	s_addc_u32 s0, s53, 0
	v_writelane_b32 v254, s0, 18
	s_mov_b32 s0, s36
	v_writelane_b32 v254, s0, 19
	s_nop 1
	v_writelane_b32 v254, s1, 20
	s_lshl_b64 s[0:1], s[36:37], 4
	v_writelane_b32 v254, s0, 21
	s_nop 1
	v_writelane_b32 v254, s1, 22
	s_add_u32 s0, s52, 0xef00180
	v_writelane_b32 v254, s0, 23
	s_addc_u32 s0, s53, 0
	v_writelane_b32 v254, s0, 24
	s_lshl_b32 s0, s42, 2
	v_writelane_b32 v254, s0, 25
	s_lshl_b32 s0, s58, 2
	v_writelane_b32 v254, s0, 26
	s_add_u32 s0, s52, 0xf00180
	v_writelane_b32 v254, s0, 27
	s_addc_u32 s0, s53, 0
	v_writelane_b32 v254, s0, 28
	s_lshl_b32 s0, s42, 6
	s_or_b32 s0, s0, 3
	v_writelane_b32 v254, s0, 29
	s_lshl_b32 s0, s58, 11
	s_add_i32 s0, s0, 0xfffe0000
	v_writelane_b32 v254, s0, 30
	s_add_i32 s0, s19, 0x7fffe200
	v_writelane_b32 v254, s0, 31
	s_lshl_b32 s0, s58, 6
	v_writelane_b32 v254, s0, 32
	s_lshl_b32 s0, s58, 5
	v_writelane_b32 v254, s0, 33
	v_writelane_b32 v254, s3, 34
	s_add_i32 s0, s3, 0xfffc0000
	v_writelane_b32 v254, s0, 35
	s_add_i32 s0, s33, 0xfffffc00
	v_writelane_b32 v254, s0, 36
	v_writelane_b32 v254, s35, 37
	s_lshl_b32 s0, s35, 5
	v_writelane_b32 v254, s0, 38
	s_add_i32 s0, s93, 0xffffc000
	v_writelane_b32 v254, s0, 39
	s_add_i32 s0, s14, 0xfffffc00
	v_writelane_b32 v254, s0, 40
	v_writelane_b32 v254, s33, 41
	s_sub_i32 s0, 0x200, s33
	s_lshl_b32 s2, s42, 5
	v_writelane_b32 v254, s0, 42
	s_sub_i32 s0, 0x200, s92
	v_writelane_b32 v254, s0, 43
	s_add_u32 s0, s52, 0xbd00180
	v_writelane_b32 v254, s0, 44
	s_addc_u32 s0, s53, 0
	v_writelane_b32 v254, s0, 45
	s_add_u32 s0, s52, 0x4300180
	v_writelane_b32 v254, s0, 46
	s_addc_u32 s0, s53, 0
	v_writelane_b32 v254, s0, 47
	s_lshl_b32 s0, s42, 8
	s_lshl_b32 s1, s4, 5
	s_add_i32 s0, s0, s1
	v_writelane_b32 v254, s0, 48
	s_lshl_b32 s0, s4, 2
	v_writelane_b32 v254, s2, 49
	s_add_i32 s0, s2, s0
	s_ashr_i32 s21, s20, 31
	v_writelane_b32 v254, s0, 50
	s_lshl_b64 s[0:1], s[20:21], 5
	v_writelane_b32 v254, s0, 51
	s_movk_i32 s33, 0x1c00
	s_mov_b32 s35, 0
	v_writelane_b32 v254, s1, 52
	s_add_u32 s0, s52, 0xb000000
	v_writelane_b32 v254, s0, 53
	s_addc_u32 s0, s53, 0
	v_writelane_b32 v254, s0, 54
	s_mov_b32 s0, s20
	v_writelane_b32 v254, s0, 55
	s_ashr_i32 s23, s22, 31
	s_ashr_i32 s15, s14, 31
	v_writelane_b32 v254, s1, 56
	s_lshl_b64 s[0:1], s[20:21], 4
	v_writelane_b32 v254, s0, 57
	s_nop 1
	v_writelane_b32 v254, s1, 58
	v_writelane_b32 v254, s22, 59
	s_lshl_b64 s[0:1], s[22:23], 6
	s_add_u32 s0, s52, s0
	s_addc_u32 s1, s53, s1
	v_writelane_b32 v254, s23, 60
	s_add_u32 s0, s0, 0x8600000
	v_writelane_b32 v254, s0, 61
	s_addc_u32 s0, s1, 0
	v_writelane_b32 v254, s0, 62
	v_writelane_b32 v254, s14, 63
	s_lshl_b64 s[0:1], s[14:15], 6
	s_nop 0
	v_writelane_b32 v255, s15, 0
	v_writelane_b32 v255, s0, 1
	s_nop 1
	v_writelane_b32 v255, s1, 2
	s_add_u32 s0, s52, 0x8510000
	v_writelane_b32 v255, s0, 3
	s_addc_u32 s0, s53, 0
	v_writelane_b32 v255, s0, 4
	s_xor_b64 s[0:1], s[6:7], -1
	v_writelane_b32 v255, s0, 5
	s_nop 1
	v_writelane_b32 v255, s1, 6
	s_add_i32 s0, 0, 0x23020
	v_writelane_b32 v255, s0, 7
	s_add_i32 s0, 0, 0x23024
	v_writelane_b32 v255, s0, 8
	v_writelane_b32 v255, s58, 9
	v_writelane_b32 v255, s59, 10
	v_writelane_b32 v255, s92, 11
	v_writelane_b32 v255, s94, 12
	s_nop 1
	v_writelane_b32 v255, s95, 13
	v_writelane_b32 v255, s56, 14
	v_writelane_b32 v255, s57, 15
	v_writelane_b32 v255, s93, 16
	s_branch .LBB0_22

; template <class Epi, class Sched, bool ALIGN_EPI = false, bool SP2 = false>
; __device__ __forceinline__ void gemm_phase(PG8_LAS unsigned char* lds, const Gemm g, const Sched& S, const Epi& E) {
;     ...
;     const int tid = tid_, wid = __builtin_amdgcn_readfirstlane(tid >> 6), lane = tid & 63, wr = wid >> 2, wc = wid & 3, fr = lane & 15, fq = lane >> 4;
;     const int K = g.K, nt = K / BK;
;     unsigned voffA[2], voffB[2];
; #pragma unroll
;     for (int i = 0; i < 2; ++i) { int R, C; stage_rc(tid * 16 + i * 8192, R, C); const int Rb = Epi::PERM ? ((R & ~31) + perm32(R & 31)) : R;
;         voffA[i] = (unsigned)(R * K + C) * 2u; voffB[i] = (unsigned)(Rb * K + C) * 2u; }
;     const size_t kstep = (size_t)(BK * 2);
;     const size_t hstep = (size_t)HALF * K * 2;
;     const size_t tstep = 2 * hstep;
;     const unsigned ldsw = (unsigned)wid * 1024u;
;     const int aoff = lds_byte(wr * 64 + fr, fq * 8), boff = lds_byte(wc * 32 + fr, fq * 8);
;     ...
;     Unit cur, nxt; int ui = 0;
;     if (!S.next(0, cur)) return;
;     f32x4 acc[2][2][4][2];
; #pragma unroll
;     for (int a = 0; a < 2; ++a)
; #pragma unroll
;         for (int b = 0; b < 2; ++b)
; #pragma unroll
;             for (int m = 0; m < 4; ++m)
; #pragma unroll
;                 for (int n = 0; n < 2; ++n) acc[a][b][m][n] = (f32x4){0.f, 0.f, 0.f, 0.f};
;     bf16x8 At[4][2], B0[2][2], B1[2][2];
;     const char* cA = (const char*)g.A + (size_t)cur.pm * tstep; const char* cB = (const char*)g.Bt + (size_t)cur.pn * tstep;
;     S.a_ready(cur);
;     if constexpr (SP2) {
;         PG8_STAGE(PG8_SB(0, 0), cB, voffB); PG8_STAGE(PG8_SB(0, 1), cB + hstep, voffB); PG8_STAGE(PG8_SA(0, 0), cA, voffA); PG8_STAGE(PG8_SA(0, 1), cA + hstep, voffA);
;         if (wr == 1) PG8_BAR;
;         PG8_WAIT_V(2); PG8_BAR;
;         PG8_STAGE(PG8_SB(1, 0), cB + kstep, voffB); PG8_STAGE(PG8_SA(1, 0), cA + kstep, voffA); PG8_STAGE(PG8_SB(1, 1), cB + hstep + kstep, voffB);
;         PG8_WAIT_V(6); PG8_BAR;
;     } else {
;         PG8_STAGE(PG8_SB(0, 0), cB, voffB); PG8_STAGE(PG8_SA(0, 0), cA, voffA); PG8_STAGE(PG8_SB(0, 1), cB + hstep, voffB); PG8_STAGE(PG8_SA(0, 1), cA + hstep, voffA);
;         if (wr == 1) PG8_BAR;
;         PG8_WAIT_V(4); PG8_BAR;
;         PG8_STAGE(PG8_SB(1, 0), cB + kstep, voffB); PG8_STAGE(PG8_SA(1, 0), cA + kstep, voffA); PG8_STAGE(PG8_SB(1, 1), cB + hstep + kstep, voffB);
.LBB0_23:
	s_add_i32 s0, s54, -1
	s_mul_hi_i32 s1, s0, 0x66666667
	s_lshr_b32 s2, s1, 31
	s_ashr_i32 s1, s1, 1
	s_add_i32 s4, s1, s2
	s_mov_b32 s2, s4
	v_writelane_b32 v255, s2, 19
	s_mul_i32 s1, s4, 5
	s_mov_b64 s[10:11], 0
	v_writelane_b32 v255, s3, 20
	s_sub_i32 s2, s0, s1
	v_writelane_b32 v255, s2, 21
	v_writelane_b32 v255, s48, 23
	s_mov_b64 s[0:1], -1
	s_cmp_lt_i32 s2, 2
	s_mov_b64 s[22:23], 0
	v_writelane_b32 v255, s49, 24
	s_cbranch_scc1 .LBB0_251
	v_readlane_b32 s0, v255, 21
	s_cmp_gt_i32 s0, 2
	s_cbranch_scc0 .LBB0_43
	s_cmp_eq_u32 s0, 3
	s_mov_b64 s[22:23], -1
	s_cbranch_scc0 .LBB0_44
	v_readlane_b32 s0, v255, 19
	s_add_u32 s7, s48, 0x1700000
	v_readlane_b32 s1, v255, 20
	s_addc_u32 s28, s49, 0
	s_ashr_i32 s1, s0, 31
	v_writelane_b32 v255, s0, 19
	v_mov_b32_e32 v9, v216
	s_nop 0
	v_writelane_b32 v255, s1, 20
	v_readlane_b32 s0, v251, 5
	v_readlane_b32 s1, v251, 6
	s_andn2_b64 vcc, exec, s[0:1]
	v_readfirstlane_b32 s2, v9
	s_cbranch_vccnz .LBB0_46
	v_lshlrev_b32_e32 v0, 4, v9
	v_add_u32_e32 v1, 0x2000, v0
	v_ashrrev_i32_e32 v2, 31, v1
	v_lshrrev_b32_e32 v2, 22, v2
	v_add_u32_e32 v2, v1, v2
	v_ashrrev_i32_e32 v8, 10, v2
	v_mul_i32_i24_e32 v2, 0x400, v8
	v_sub_u32_e32 v1, v1, v2
	v_lshrrev_b32_e32 v2, 4, v1
	v_bitop3_b32 v1, v2, v1, 32 bitop3:0x6c
	v_ashrrev_i32_e32 v2, 31, v1
	v_lshrrev_b32_e32 v2, 26, v2
	s_add_u32 s29, s48, 0x5d00000
	v_readlane_b32 s4, v255, 19
	v_add_u32_e32 v2, v1, v2
	v_lshlrev_b32_e32 v3, 3, v8
	s_addc_u32 s30, s49, 0
	s_mul_i32 s1, s4, 0xb00000
	v_ashrrev_i32_e32 v10, 6, v2
	v_and_b32_e32 v3, -16, v3
	s_mul_hi_i32 s0, s4, 0xb00000
	s_add_u32 s31, s7, s1
	v_add_u32_e32 v3, v10, v3
	s_addc_u32 s38, s28, s0
	v_and_b32_e32 v4, 3, v10
	s_mov_b32 s0, 0x1fffe0
	v_lshrrev_b32_e32 v5, 2, v3
	v_lshlrev_b32_e32 v6, 1, v3
	v_and_b32_e32 v2, 0xc0, v2
	v_and_or_b32 v4, v3, s0, v4
	v_and_b32_e32 v5, 4, v5
	v_and_b32_e32 v6, 24, v6
	v_sub_u32_e32 v1, v1, v2
	v_or3_b32 v4, v4, v5, v6
	v_lshlrev_b32_e32 v5, 5, v8
	v_ashrrev_i16_sdwa v1, v221, sext(v1) dst_sel:DWORD dst_unused:UNUSED_PAD src0_sel:DWORD src1_sel:BYTE_0
	v_and_b32_e32 v5, 32, v5
	v_bfe_i32 v11, v1, 0, 16
	v_add_lshl_u32 v1, v5, v11, 1
	v_lshl_add_u32 v128, v4, 11, v1
	v_lshl_add_u32 v130, v3, 11, v1
	v_bfe_i32 v1, v9, 27, 1
	v_lshrrev_b32_e32 v1, 22, v1
	v_add_u32_e32 v1, v0, v1
	v_and_b32_e32 v1, 0xfffffc00, v1
	v_sub_u32_e32 v0, v0, v1
	v_lshrrev_b32_e32 v1, 4, v0
	v_ashrrev_i32_e32 v2, 31, v9
	v_bitop3_b32 v0, v1, v0, 32 bitop3:0x6c
	v_lshrrev_b32_e32 v2, 26, v2
	v_ashrrev_i32_e32 v1, 31, v0
	v_add_u32_e32 v2, v9, v2
	v_lshrrev_b32_e32 v1, 26, v1
	v_ashrrev_i32_e32 v13, 6, v2
	v_add_u32_e32 v1, v0, v1
	v_lshlrev_b32_e32 v2, 3, v13
	v_ashrrev_i32_e32 v12, 6, v1
	v_and_b32_e32 v2, -16, v2
	v_add_u32_e32 v2, v12, v2
	v_and_b32_e32 v3, 3, v12
	v_lshrrev_b32_e32 v4, 2, v2
	v_lshlrev_b32_e32 v5, 1, v2
	v_and_b32_e32 v1, 0xc0, v1
	s_ashr_i32 s4, s2, 6
	v_and_or_b32 v3, v2, s0, v3
	v_and_b32_e32 v4, 4, v4
	v_and_b32_e32 v5, 24, v5
	v_sub_u32_e32 v0, v0, v1
	s_ashr_i32 s3, s2, 8
	s_lshl_b32 s39, s4, 10
	v_or3_b32 v3, v3, v4, v5
	v_lshlrev_b32_e32 v4, 5, v13
	v_ashrrev_i16_sdwa v0, v221, sext(v0) dst_sel:DWORD dst_unused:UNUSED_PAD src0_sel:DWORD src1_sel:BYTE_0
	v_readlane_b32 s98, v251, 0
	v_and_b32_e32 v4, 32, v4
	v_bfe_i32 v14, v0, 0, 16
	s_nop 0
	s_lshr_b32 s0, s98, 6
	s_lshl_b32 s0, s0, 19
	s_mov_b32 s1, 0
	s_add_u32 s24, s31, s0
	v_add_lshl_u32 v0, v4, v14, 1
	s_addc_u32 s25, s38, s1
	s_add_i32 s40, s39, 0
	v_lshl_add_u32 v132, v3, 11, v0
	s_add_i32 m0, s40, 0x10000
	v_lshl_add_u32 v134, v2, 11, v0
	global_load_lds_dwordx4 v132, s[24:25]
	s_add_i32 m0, s40, 0x12000
	s_add_u32 s0, s24, 0x40000
	global_load_lds_dwordx4 v128, s[24:25]
	s_addc_u32 s1, s25, 0
	s_add_i32 m0, s40, 0x14000
	s_mov_b64 s[94:95], s[54:55]
	global_load_lds_dwordx4 v132, s[0:1]
	s_add_i32 m0, s40, 0x16000
	v_mov_b32_e32 v133, v185
	global_load_lds_dwordx4 v128, s[0:1]
	v_readlane_b32 s98, v251, 0
	s_nop 0
	s_and_b32 s0, s98, 7
	s_lshl_b32 s0, s0, 3
	s_bfe_u32 s1, s98, 0x30003
	s_add_i32 s0, s0, s1
	s_mul_i32 s0, s0, 0x90000
	s_mov_b32 s1, 0
	s_add_u32 s0, s29, s0
	s_addc_u32 s1, s30, s1
	s_add_i32 s41, s40, 0x2000
	s_mov_b32 m0, s40
	s_add_u32 s8, s0, 0x40000
	global_load_lds_dwordx4 v134, s[0:1]
	s_mov_b32 m0, s41
	s_addc_u32 s9, s1, 0
	s_add_i32 s42, s40, 0x4000
	global_load_lds_dwordx4 v130, s[0:1]
	s_lshr_b32 s98, s39, 12
	s_mul_i32 s98, s98, 0x10000
	s_sub_u32 s98, 0x80000, s98
	v_add_u32_e32 v248, s98, v134
	s_and_b32 m0, s39, 0xc00
	s_add_i32 m0, m0, 0x20800
	s_nop 0
	global_load_lds_dwordx4 v248, s[0:1]
	s_mov_b32 m0, s42
	s_add_i32 s43, s40, 0x6000
	global_load_lds_dwordx4 v134, s[8:9]
	s_mov_b32 m0, s43
	v_mov_b32_e32 v129, v185
	global_load_lds_dwordx4 v130, s[8:9]
	v_mov_b32_e32 v135, v185
	v_mov_b32_e32 v131, v185
	s_cmp_eq_u32 s3, 1
	s_mov_b64 s[92:93], s[52:53]
	v_lshl_add_u64 v[6:7], s[24:25], 0, v[132:133]
	v_lshl_add_u64 v[4:5], s[24:25], 0, v[128:129]
	v_lshl_add_u64 v[0:1], s[0:1], 0, v[134:135]
	s_cselect_b64 s[8:9], -1, 0
	s_cmp_lg_u32 s3, 1
	v_lshl_add_u64 v[2:3], s[0:1], 0, v[130:131]
	v_readlane_b32 s5, v255, 20
	s_cbranch_scc1 .LBB0_29
	s_barrier
; #define PG8_STAGE(bufoff, gbase, voff) do { _Pragma("unroll") for (int _i = 0; _i < 2; ++_i) \
;         __builtin_amdgcn_global_load_lds((const unsigned*)((const char*)(gbase) + (voff)[_i]), (PG8_LAS unsigned*)(lds + (bufoff) + ldsw + _i * 8192), 16, 0, 0); } while (0)
; #define PG8_WAIT_V(n) asm volatile("s_waitcnt vmcnt(" #n ")" ::: "memory")
; #define PG8_BAR __builtin_amdgcn_s_barrier()
; template <class Epi, class Sched, bool ALIGN_EPI = false, bool SP2 = false>
; __device__ __forceinline__ void gemm_phase(PG8_LAS unsigned char* lds, const Gemm g, const Sched& S, const Epi& E) {
;     ...
;     const int aoff = lds_byte(wr * 64 + fr, fq * 8), boff = lds_byte(wc * 32 + fr, fq * 8);
;     ...
;     Unit cur, nxt; int ui = 0;
;     if (!S.next(0, cur)) return;
;     f32x4 acc[2][2][4][2];
; #pragma unroll
;     for (int a = 0; a < 2; ++a)
; #pragma unroll
;         for (int b = 0; b < 2; ++b)
; #pragma unroll
;             for (int m = 0; m < 4; ++m)
; #pragma unroll
;                 for (int n = 0; n < 2; ++n) acc[a][b][m][n] = (f32x4){0.f, 0.f, 0.f, 0.f};
;     bf16x8 At[4][2], B0[2][2], B1[2][2];
;     const char* cA = (const char*)g.A + (size_t)cur.pm * tstep; const char* cB = (const char*)g.Bt + (size_t)cur.pn * tstep;
;     S.a_ready(cur);
;     if constexpr (SP2) {
;         PG8_STAGE(PG8_SB(0, 0), cB, voffB); PG8_STAGE(PG8_SB(0, 1), cB + hstep, voffB); PG8_STAGE(PG8_SA(0, 0), cA, voffA); PG8_STAGE(PG8_SA(0, 1), cA + hstep, voffA);
;         if (wr == 1) PG8_BAR;
;         PG8_WAIT_V(2); PG8_BAR;
;         PG8_STAGE(PG8_SB(1, 0), cB + kstep, voffB); PG8_STAGE(PG8_SA(1, 0), cA + kstep, voffA); PG8_STAGE(PG8_SB(1, 1), cB + hstep + kstep, voffB);
;         PG8_WAIT_V(6); PG8_BAR;
.LBB0_29:
	s_lshl_b32 s4, s4, 5
	s_and_b32 s18, s4, 0x60
	s_add_i32 m0, s40, 0x18000
	v_lshl_add_u64 v[6:7], v[6:7], 0, s[96:97]
	s_lshl_b32 s12, s3, 13
	s_lshl_b32 s13, s18, 7
	s_waitcnt vmcnt(2)
	s_barrier
	global_load_lds_dwordx4 v[6:7], off
	v_lshl_add_u64 v[4:5], v[4:5], 0, s[96:97]
	s_add_i32 m0, s40, 0x1a000
	s_add_i32 s44, s40, 0x8000
	s_add_i32 s45, s40, 0xa000
	global_load_lds_dwordx4 v[4:5], off
	v_lshl_add_u64 v[0:1], v[0:1], 0, s[96:97]
	s_mov_b32 m0, s44
	s_add_u32 s4, s24, 0x40080
	global_load_lds_dwordx4 v[0:1], off
	v_lshl_add_u64 v[0:1], v[2:3], 0, s[96:97]
	s_mov_b32 m0, s45
	s_addc_u32 s5, s25, 0
	global_load_lds_dwordx4 v[0:1], off
	s_add_i32 m0, s40, 0x1c000
	v_lshl_add_u64 v[0:1], s[4:5], 0, v[132:133]
	global_load_lds_dwordx4 v[0:1], off
	v_lshl_add_u64 v[0:1], s[4:5], 0, v[128:129]
	s_add_i32 m0, s40, 0x1e000
	s_cmpk_lt_u32 s2, 0x100
	global_load_lds_dwordx4 v[0:1], off
	v_lshrrev_b32_e32 v0, 1, v9
	v_and_b32_e32 v0, 24, v0
	v_and_b32_e32 v1, 15, v9
	v_lshlrev_b32_e32 v2, 1, v0
	v_lshl_or_b32 v140, s3, 6, v1
	v_lshl_or_b32 v2, v1, 6, v2
	v_lshlrev_b32_e32 v1, 2, v1
	v_and_b32_e32 v3, 32, v1
	v_bitop3_b32 v4, v2, s12, v3 bitop3:0xde
	v_bitop3_b32 v141, v2, s13, v3 bitop3:0xde
	s_cselect_b64 s[12:13], -1, 0
	s_add_u32 s98, s0, 0x80
	s_addc_u32 s99, s1, 0
	s_and_b32 m0, s39, 0xc00
	s_add_i32 m0, m0, 0x21800
	s_nop 0
	global_load_lds_dwordx4 v248, s[98:99]
	s_add_u32 s14, s48, 0x8600000
	s_addc_u32 s15, s49, 0
	s_lshl_b32 s2, s3, 8
	s_add_i32 s2, s2, 0
	s_add_i32 s2, s2, 0x20000
	v_add_u32_e32 v142, s2, v1
	v_lshlrev_b32_e32 v1, 14, v13
	v_and_b32_e32 v1, 0xffff8000, v1
	v_lshl_add_u32 v1, v12, 11, v1
	v_and_b32_e32 v2, 1, v13
	v_lshl_or_b32 v1, v2, 6, v1
	v_lshl_add_u32 v136, v14, 1, v1
	v_lshlrev_b32_e32 v1, 14, v8
	v_and_b32_e32 v1, 0xffff8000, v1
	s_waitcnt vmcnt(7)
	v_lshl_add_u32 v1, v10, 11, v1
	v_and_b32_e32 v2, 1, v8
	s_add_u32 s16, s48, 0xbd00000
	v_lshl_or_b32 v1, v2, 6, v1
	s_addc_u32 s17, s49, 0
	v_readlane_b32 s98, v251, 0
	s_nop 0
	s_and_b32 s2, s98, 7
	s_lshl_b32 s2, s2, 3
	s_bfe_u32 s99, s98, 0x30003
	s_add_i32 s2, s2, s99
	v_mov_b32_e32 v137, v185
	v_lshl_add_u32 v138, v11, 1, v1
	v_mov_b32_e32 v139, v185
	s_mov_b32 s46, 0
	v_add_u32_e32 v143, 0, v4
	s_lshr_b32 s98, s39, 12
	s_mul_i32 s98, s98, 0x1800
	s_sub_u32 s98, 0x20800, s98
	v_add_u32_e32 v249, s98, v143
	s_lshl_b32 s34, s18, 1
	v_lshlrev_b32_e32 v184, 1, v0
	v_readlane_b32 s98, v251, 0
	s_nop 0
	s_lshr_b32 s47, s98, 6
	s_mov_b32 s48, s2
	s_barrier
	v_readlane_b32 s3, v253, 62
	s_branch .LBB0_32

;     __host__ __device__ bool next(int i, Unit& u) const {
;         const long L = (long)i * G + c; if (L >= nwg) return false;
;         int wgid = (int)L; { const int q = nwg / NXCD, r = nwg % NXCD, xcd = wgid % NXCD, off = wgid / NXCD; wgid = (xcd < r ? xcd * (q + 1) : r * (q + 1) + (xcd - r) * q) + off; }
;         const int nig = WGM * nN, gid = wgid / nig, fm = gid * WGM, gsz = (nM - fm) < WGM ? (nM - fm) : WGM;
;         u.pm = fm + ((wgid % nig) % gsz); u.pn = (wgid % nig) / gsz; return true;
; template <class Epi, class Sched, bool ALIGN_EPI = false, bool SP2 = false>
; __device__ __forceinline__ void gemm_phase(PG8_LAS unsigned char* lds, const Gemm g, const Sched& S, const Epi& E) {
;     ...
; #pragma unroll
;         for (int a = 0; a < 2; ++a)
; #pragma unroll
;             for (int b = 0; b < 2; ++b)
; #pragma unroll
;                 for (int m = 0; m < 4; ++m)
; #pragma unroll
;                     for (int n = 0; n < 2; ++n) acc[a][b][m][n] = (f32x4){0.f, 0.f, 0.f, 0.f};
.LBB0_32:
	s_add_i32 s46, s46, 1
	v_readlane_b32 s3, v251, 7
	s_mul_i32 s3, s46, s3
	s_mul_hi_u32 s4, s46, s58
	s_add_i32 s3, s4, s3
	s_mul_i32 s4, s46, s58
	v_readlane_b32 s5, v251, 0
	s_add_u32 s4, s4, s5
	s_addc_u32 s5, s3, s59
	s_cmp_lt_u32 s4, 0x500
	s_cbranch_scc1 .Lgu_sch_done
	s_sub_u32 s98, s4, 0x500
	s_cmp_lt_u32 s98, 48
	s_cbranch_scc1 .Lgu_sch_done
	s_cmp_ge_u32 s98, 0xb0
	s_cbranch_scc0 .Lgu_sch_inv
	s_sub_u32 s4, s4, 0x80
	s_branch .Lgu_sch_done
.Lgu_sch_inv:
	s_mov_b32 s4, 0x580
.Lgu_sch_done:
	v_mov_b64_e32 v[0:1], 0x580
	v_cmp_lt_i64_e64 s[36:37], s[4:5], v[0:1]
	v_mov_b64_e32 v[0:1], 0x57f
	v_cmp_gt_i64_e32 vcc, s[4:5], v[0:1]
	s_cbranch_vccnz .LBB0_34
	s_ashr_i32 s2, s4, 31
	s_lshr_b32 s2, s2, 29
	s_add_i32 s2, s4, s2
	s_ashr_i32 s3, s2, 3
	s_and_b32 s2, s2, -8
	s_sub_i32 s2, s4, s2
	s_cmp_lt_i32 s2, 0
	s_movk_i32 s4, 0xc7
	s_movk_i32 s4, 0xb0
	s_mul_i32 s2, s2, s4
	s_add_i32 s2, s2, s3
	s_mul_hi_i32 s3, s2, 0x2e8ba2e9
	s_lshr_b32 s4, s3, 31
	s_ashr_i32 s3, s3, 5
	s_add_i32 s3, s3, s4
	s_lshl_b32 s4, s3, 3
	s_sub_i32 s5, 64, s4
	s_min_i32 s5, s5, 8
	s_abs_i32 s18, s5
	v_cvt_f32_u32_e32 v0, s18
	s_sub_i32 s20, 0, s18
	s_mulk_i32 s3, 0xb0
	s_sub_i32 s3, s2, s3
	v_rcp_iflag_f32_e32 v0, v0
	s_abs_i32 s2, s3
	s_xor_b32 s19, s3, s5
	s_ashr_i32 s19, s19, 31
	v_mul_f32_e32 v0, 0x4f7ffffe, v0
	v_cvt_u32_f32_e32 v0, v0
	s_nop 0
	v_readfirstlane_b32 s21, v0
	s_mul_i32 s20, s20, s21
	s_mul_hi_u32 s20, s21, s20
	s_add_i32 s21, s21, s20
	s_mul_hi_u32 s20, s2, s21
	s_mul_i32 s21, s20, s18
	s_sub_i32 s2, s2, s21
	s_add_i32 s22, s20, 1
	s_sub_i32 s21, s2, s18
	s_cmp_ge_u32 s2, s18
	s_cselect_b32 s20, s22, s20
	s_cselect_b32 s2, s21, s2
	s_add_i32 s21, s20, 1
	s_cmp_ge_u32 s2, s18
	s_cselect_b32 s2, s21, s20
	s_xor_b32 s2, s2, s19
	s_sub_i32 s2, s2, s19
	s_mul_i32 s5, s2, s5
	s_sub_i32 s3, s3, s5
	s_add_i32 s18, s4, s3
.LBB0_34:
	s_ashr_i32 s19, s18, 31
	s_mul_i32 s4, s18, 0x90000
	s_mov_b32 s5, 0
	s_add_u32 s20, s29, s4
	s_addc_u32 s21, s30, s5
	s_and_b64 s[4:5], s[36:37], exec
	s_cselect_b32 s4, s21, s1
	s_cselect_b32 s5, s20, s0
	s_ashr_i32 s3, s2, 31
	s_lshl_b64 s[22:23], s[2:3], 19
	s_add_u32 s22, s31, s22
	s_addc_u32 s23, s38, s23
	s_and_b64 s[26:27], s[36:37], exec
	s_cselect_b32 s3, s23, s25
	s_cselect_b32 s19, s22, s24
	s_add_u32 s0, s0, 0x40080
	s_addc_u32 s1, s1, 0
	s_add_u32 s49, s24, 0x100
	v_mov_b32_e32 v0, 0
	s_addc_u32 s50, s25, 0
	s_mov_b32 s51, -2
	v_mov_b32_e32 v1, v0
	v_mov_b32_e32 v2, v0
	v_mov_b32_e32 v3, v0
	v_mov_b32_e32 v8, v0
	v_mov_b32_e32 v9, v0
	v_mov_b32_e32 v10, v0
	v_mov_b32_e32 v11, v0
	v_mov_b32_e32 v16, v0
	v_mov_b32_e32 v17, v0
	v_mov_b32_e32 v18, v0
	v_mov_b32_e32 v19, v0
	v_mov_b32_e32 v24, v0
	v_mov_b32_e32 v25, v0
	v_mov_b32_e32 v26, v0
	v_mov_b32_e32 v27, v0
	v_mov_b32_e32 v32, v0
	v_mov_b32_e32 v33, v0
	v_mov_b32_e32 v34, v0
	v_mov_b32_e32 v35, v0
	v_mov_b32_e32 v40, v0
	v_mov_b32_e32 v41, v0
	v_mov_b32_e32 v42, v0
	v_mov_b32_e32 v43, v0
	v_mov_b32_e32 v48, v0
	v_mov_b32_e32 v49, v0
	v_mov_b32_e32 v50, v0
	v_mov_b32_e32 v51, v0
	v_mov_b32_e32 v56, v0
	v_mov_b32_e32 v57, v0
	v_mov_b32_e32 v58, v0
	v_mov_b32_e32 v59, v0
	v_mov_b32_e32 v4, v0
	v_mov_b32_e32 v5, v0
	v_mov_b32_e32 v6, v0
	v_mov_b32_e32 v7, v0
	v_mov_b32_e32 v12, v0
	v_mov_b32_e32 v13, v0
	v_mov_b32_e32 v14, v0
	v_mov_b32_e32 v15, v0
	v_mov_b32_e32 v20, v0
	v_mov_b32_e32 v21, v0
	v_mov_b32_e32 v22, v0
	v_mov_b32_e32 v23, v0
	v_mov_b32_e32 v28, v0
	v_mov_b32_e32 v29, v0
	v_mov_b32_e32 v30, v0
	v_mov_b32_e32 v31, v0
	v_mov_b32_e32 v36, v0
	v_mov_b32_e32 v37, v0
	v_mov_b32_e32 v38, v0
	v_mov_b32_e32 v39, v0
	v_mov_b32_e32 v44, v0
	v_mov_b32_e32 v45, v0
	v_mov_b32_e32 v46, v0
	v_mov_b32_e32 v47, v0
	v_mov_b32_e32 v52, v0
	v_mov_b32_e32 v53, v0
	v_mov_b32_e32 v54, v0
	v_mov_b32_e32 v55, v0
	v_mov_b32_e32 v60, v0
	v_mov_b32_e32 v61, v0
	v_mov_b32_e32 v62, v0
	v_mov_b32_e32 v63, v0
	v_mov_b32_e32 v64, v0
	v_mov_b32_e32 v65, v0
	v_mov_b32_e32 v66, v0
	v_mov_b32_e32 v67, v0
	v_mov_b32_e32 v72, v0
	v_mov_b32_e32 v73, v0
	v_mov_b32_e32 v74, v0
	v_mov_b32_e32 v75, v0
	v_mov_b32_e32 v80, v0
	v_mov_b32_e32 v81, v0
	v_mov_b32_e32 v82, v0
	v_mov_b32_e32 v83, v0
	v_mov_b32_e32 v88, v0
	v_mov_b32_e32 v89, v0
	v_mov_b32_e32 v90, v0
	v_mov_b32_e32 v91, v0
	v_mov_b32_e32 v96, v0
	v_mov_b32_e32 v97, v0
	v_mov_b32_e32 v98, v0
	v_mov_b32_e32 v99, v0
	v_mov_b32_e32 v104, v0
	v_mov_b32_e32 v105, v0
	v_mov_b32_e32 v106, v0
	v_mov_b32_e32 v107, v0
	v_mov_b32_e32 v112, v0
	v_mov_b32_e32 v113, v0
	v_mov_b32_e32 v114, v0
	v_mov_b32_e32 v115, v0
	v_mov_b32_e32 v120, v0
	v_mov_b32_e32 v121, v0
	v_mov_b32_e32 v122, v0
	v_mov_b32_e32 v123, v0
	v_mov_b32_e32 v68, v0
	v_mov_b32_e32 v69, v0
	v_mov_b32_e32 v70, v0
	v_mov_b32_e32 v71, v0
	v_mov_b32_e32 v76, v0
	v_mov_b32_e32 v77, v0
	v_mov_b32_e32 v78, v0
	v_mov_b32_e32 v79, v0
	v_mov_b32_e32 v84, v0
	v_mov_b32_e32 v85, v0
	v_mov_b32_e32 v86, v0
	v_mov_b32_e32 v87, v0
	v_mov_b32_e32 v92, v0
	v_mov_b32_e32 v93, v0
	v_mov_b32_e32 v94, v0
	v_mov_b32_e32 v95, v0
	v_mov_b32_e32 v100, v0
	v_mov_b32_e32 v101, v0
	v_mov_b32_e32 v102, v0
	v_mov_b32_e32 v103, v0
	v_mov_b32_e32 v108, v0
	v_mov_b32_e32 v109, v0
	v_mov_b32_e32 v110, v0
	v_mov_b32_e32 v111, v0
	v_mov_b32_e32 v116, v0
	v_mov_b32_e32 v117, v0
	v_mov_b32_e32 v118, v0
	v_mov_b32_e32 v119, v0
	v_mov_b32_e32 v124, v0
	v_mov_b32_e32 v125, v0
	v_mov_b32_e32 v126, v0
	v_mov_b32_e32 v127, v0
	v_mov_b32_e32 v236, v0
	v_mov_b32_e32 v237, v0
	v_mov_b32_e32 v238, v0
	v_mov_b32_e32 v239, v0
	v_mov_b32_e32 v240, v0
	v_mov_b32_e32 v241, v0
	v_mov_b32_e32 v242, v0
	v_mov_b32_e32 v243, v0
	v_mov_b32_e32 v244, v0
	v_mov_b32_e32 v245, v0
	v_mov_b32_e32 v246, v0
	v_mov_b32_e32 v247, v0
	v_mov_b32_e32 v224, v0
	v_mov_b32_e32 v225, v0
	v_mov_b32_e32 v226, v0
	v_mov_b32_e32 v227, v0
; #define PG8_STAGE(bufoff, gbase, voff) do { _Pragma("unroll") for (int _i = 0; _i < 2; ++_i) \
;         __builtin_amdgcn_global_load_lds((const unsigned*)((const char*)(gbase) + (voff)[_i]), (PG8_LAS unsigned*)(lds + (bufoff) + ldsw + _i * 8192), 16, 0, 0); } while (0)
; #define PG8_LDA(dst, b, h) do { _Pragma("unroll") for (int m = 0; m < 4; ++m) _Pragma("unroll") for (int k = 0; k < 2; ++k) dst[m][k] = *(const PG8_LAS bf16x8*)(lds + PG8_SA(b, h) + aoff + m * 2048 + k * 1024); } while (0)
; #define PG8_LDB(dst, b, h) do { _Pragma("unroll") for (int n = 0; n < 2; ++n) _Pragma("unroll") for (int k = 0; k < 2; ++k) dst[n][k] = *(const PG8_LAS bf16x8*)(lds + PG8_SB(b, h) + boff + n * 2048 + k * 1024); } while (0)
; #define PG8_MMA(ai, bj, At, Bt) do { __builtin_amdgcn_s_setprio(1); _Pragma("unroll") for (int m = 0; m < 4; ++m) _Pragma("unroll") for (int n = 0; n < 2; ++n) _Pragma("unroll") for (int k = 0; k < 2; ++k) \
;         acc[ai][bj][m][n] = __builtin_amdgcn_mfma_f32_16x16x32_bf16(Bt[n][k], At[m][k], acc[ai][bj][m][n], 0, 0, 0); __builtin_amdgcn_s_setprio(0); } while (0)
; #define PG8_WAIT_V(n) asm volatile("s_waitcnt vmcnt(" #n ")" ::: "memory")
; #define PG8_WAIT_L(n) asm volatile("s_waitcnt lgkmcnt(" #n ")" ::: "memory")
; #define PG8_BAR __builtin_amdgcn_s_barrier()
; #define PG8_SCHED __builtin_amdgcn_sched_barrier(0)
; template <class Epi, class Sched, bool ALIGN_EPI = false, bool SP2 = false>
; __device__ __forceinline__ void gemm_phase(PG8_LAS unsigned char* lds, const Gemm g, const Sched& S, const Epi& E) {
;     ...
;             PG8_LDB(B0, 0, 0); PG8_LDB(B1, 0, 1); PG8_SCHED; PG8_LDA(At, 0, 0); PG8_STAGE(PG8_SA(1, 1), a1 + hstep, voffA);
;             PG8_WAIT_V(8); PG8_WAIT_L(0); PG8_BAR; PG8_MMA(0, 0, At, B0); PG8_MMA(0, 1, At, B1); PG8_BAR; PG8_SCHED;
;             PG8_LDA(At, 0, 1); PG8_STAGE(PG8_SB(0, 0), b2, voffB); PG8_STAGE(PG8_SB(0, 1), b2 + hstep, voffB); PG8_STAGE(PG8_SA(0, 0), a2, voffA);
;             PG8_WAIT_V(8); PG8_WAIT_L(0); PG8_BAR; PG8_MMA(1, 0, At, B0); PG8_MMA(1, 1, At, B1); PG8_BAR; PG8_SCHED;
.LBB0_35:
	s_add_u32 s24, s0, 0xfffc0080
	s_addc_u32 s25, s1, -1
	s_cmp_eq_u32 s51, 12
	s_cselect_b32 s27, s4, s25
	s_cselect_b32 s26, s5, s24
	s_cselect_b32 s25, s3, s50
	s_cselect_b32 s24, s19, s49
	s_add_i32 s52, 0, 0x10000
	s_add_i32 s54, 0, 0x14000
	v_add_u32_e32 v156, s52, v141
	v_add_u32_e32 v172, s54, v141
	ds_read_b128 v[144:147], v156
	ds_read_b128 v[148:151], v156 offset:1024
	ds_read_b128 v[152:155], v156 offset:2048
	ds_read_b128 v[156:159], v156 offset:3072
	ds_read_b128 v[160:163], v172
	ds_read_b128 v[164:167], v172 offset:1024
	ds_read_b128 v[168:171], v172 offset:2048
	ds_read_b128 v[172:175], v172 offset:3072
	s_add_i32 m0, s40, 0xc000
	ds_read_b128 v[176:179], v143
	ds_read_b128 v[180:183], v143 offset:1024
	ds_read_b128 v[194:197], v143 offset:2048
	ds_read_b128 v[198:201], v143 offset:3072
	ds_read_b128 v[202:205], v143 offset:4096
	ds_read_b128 v[206:209], v143 offset:5120
	ds_read_b128 v[210:213], v143 offset:6144
	ds_read_b128 v[228:231], v143 offset:7168
	ds_read_b128 v[232:235], v249
	ds_read_b128 v[136:139], v249 offset:1024
	global_load_lds_dwordx4 v134, s[0:1]
	s_add_i32 m0, s40, 0xe000
	s_nop 0
	global_load_lds_dwordx4 v130, s[0:1]
	s_waitcnt vmcnt(9)
	s_waitcnt lgkmcnt(0)
	s_barrier
	s_setprio 1
	s_waitcnt lgkmcnt(0)
	v_mfma_f32_16x16x32_bf16 v[124:127], v[144:147], v[176:179], v[124:127]
	v_mfma_f32_16x16x32_bf16 v[116:119], v[152:155], v[176:179], v[116:119]
	v_mfma_f32_16x16x32_bf16 v[108:111], v[144:147], v[194:197], v[108:111]
	v_mfma_f32_16x16x32_bf16 v[100:103], v[152:155], v[194:197], v[100:103]
	v_mfma_f32_16x16x32_bf16 v[92:95], v[144:147], v[202:205], v[92:95]
	v_mfma_f32_16x16x32_bf16 v[84:87], v[152:155], v[202:205], v[84:87]
	v_mfma_f32_16x16x32_bf16 v[76:79], v[144:147], v[210:213], v[76:79]
	v_mfma_f32_16x16x32_bf16 v[68:71], v[152:155], v[210:213], v[68:71]
	v_mfma_f32_16x16x32_bf16 v[124:127], v[148:151], v[180:183], v[124:127]
	v_mfma_f32_16x16x32_bf16 v[116:119], v[156:159], v[180:183], v[116:119]
	v_mfma_f32_16x16x32_bf16 v[108:111], v[148:151], v[198:201], v[108:111]
	v_mfma_f32_16x16x32_bf16 v[100:103], v[156:159], v[198:201], v[100:103]
	v_mfma_f32_16x16x32_bf16 v[92:95], v[148:151], v[206:209], v[92:95]
	v_mfma_f32_16x16x32_bf16 v[84:87], v[156:159], v[206:209], v[84:87]
	v_mfma_f32_16x16x32_bf16 v[76:79], v[148:151], v[228:231], v[76:79]
	v_mfma_f32_16x16x32_bf16 v[68:71], v[156:159], v[228:231], v[68:71]
	s_setprio 0
	s_setprio 1
	v_mfma_f32_16x16x32_bf16 v[120:123], v[160:163], v[176:179], v[120:123]
	v_mfma_f32_16x16x32_bf16 v[112:115], v[168:171], v[176:179], v[112:115]
	v_mfma_f32_16x16x32_bf16 v[104:107], v[160:163], v[194:197], v[104:107]
	v_mfma_f32_16x16x32_bf16 v[96:99], v[168:171], v[194:197], v[96:99]
	v_mfma_f32_16x16x32_bf16 v[88:91], v[160:163], v[202:205], v[88:91]
	v_mfma_f32_16x16x32_bf16 v[80:83], v[168:171], v[202:205], v[80:83]
	v_mfma_f32_16x16x32_bf16 v[72:75], v[160:163], v[210:213], v[72:75]
	v_mfma_f32_16x16x32_bf16 v[64:67], v[168:171], v[210:213], v[64:67]
	v_mfma_f32_16x16x32_bf16 v[120:123], v[164:167], v[180:183], v[120:123]
	v_mfma_f32_16x16x32_bf16 v[112:115], v[172:175], v[180:183], v[112:115]
	v_mfma_f32_16x16x32_bf16 v[104:107], v[164:167], v[198:201], v[104:107]
	v_mfma_f32_16x16x32_bf16 v[96:99], v[172:175], v[198:201], v[96:99]
	v_mfma_f32_16x16x32_bf16 v[88:91], v[164:167], v[206:209], v[88:91]
	v_mfma_f32_16x16x32_bf16 v[80:83], v[172:175], v[206:209], v[80:83]
	v_mfma_f32_16x16x32_bf16 v[72:75], v[164:167], v[228:231], v[72:75]
	v_mfma_f32_16x16x32_bf16 v[64:67], v[172:175], v[228:231], v[64:67]
	v_mfma_f32_16x16x32_bf16 v[236:239], v[144:147], v[232:235], v[236:239]
	v_mfma_f32_16x16x32_bf16 v[240:243], v[152:155], v[232:235], v[240:243]
	v_mfma_f32_16x16x32_bf16 v[244:247], v[160:163], v[232:235], v[244:247]
	v_mfma_f32_16x16x32_bf16 v[224:227], v[168:171], v[232:235], v[224:227]
	v_mfma_f32_16x16x32_bf16 v[236:239], v[148:151], v[136:139], v[236:239]
	v_mfma_f32_16x16x32_bf16 v[240:243], v[156:159], v[136:139], v[240:243]
	v_mfma_f32_16x16x32_bf16 v[244:247], v[164:167], v[136:139], v[244:247]
	v_mfma_f32_16x16x32_bf16 v[224:227], v[172:175], v[136:139], v[224:227]
	s_setprio 0
	s_barrier
	s_add_i32 s52, s52, s39
	s_mov_b32 m0, s52
	ds_read_b128 v[176:179], v143 offset:16384
	ds_read_b128 v[180:183], v143 offset:17408
	ds_read_b128 v[194:197], v143 offset:18432
	ds_read_b128 v[198:201], v143 offset:19456
	ds_read_b128 v[202:205], v143 offset:20480
	ds_read_b128 v[206:209], v143 offset:21504
	ds_read_b128 v[210:213], v143 offset:22528
	ds_read_b128 v[228:231], v143 offset:23552
	global_load_lds_dwordx4 v132, s[24:25]
	s_add_i32 m0, s52, 0x2000
	s_add_u32 s98, s24, 0x40000
	s_addc_u32 s99, s25, 0
	s_add_i32 s54, s54, s39
	global_load_lds_dwordx4 v128, s[24:25]
	s_mov_b32 m0, s54
	s_nop 0
	global_load_lds_dwordx4 v132, s[98:99]
	s_add_i32 m0, s54, 0x2000
	s_nop 0
	global_load_lds_dwordx4 v128, s[98:99]
	s_mov_b32 m0, s40
	s_nop 0
	global_load_lds_dwordx4 v134, s[26:27]
	s_mov_b32 m0, s41
	s_nop 0
	global_load_lds_dwordx4 v130, s[26:27]
	s_and_b32 m0, s39, 0xc00
	s_add_i32 m0, m0, 0x20800
	s_nop 0
	global_load_lds_dwordx4 v248, s[26:27]
	s_waitcnt vmcnt(9)
	s_waitcnt lgkmcnt(0)
	s_barrier
; __device__ __forceinline__ float sum4(const f32x4 a) { return (a[0] + a[1]) + (a[2] + a[3]); }
; #define PG8_STAGE(bufoff, gbase, voff) do { _Pragma("unroll") for (int _i = 0; _i < 2; ++_i) \
;         __builtin_amdgcn_global_load_lds((const unsigned*)((const char*)(gbase) + (voff)[_i]), (PG8_LAS unsigned*)(lds + (bufoff) + ldsw + _i * 8192), 16, 0, 0); } while (0)
; #define PG8_LDA(dst, b, h) do { _Pragma("unroll") for (int m = 0; m < 4; ++m) _Pragma("unroll") for (int k = 0; k < 2; ++k) dst[m][k] = *(const PG8_LAS bf16x8*)(lds + PG8_SA(b, h) + aoff + m * 2048 + k * 1024); } while (0)
; #define PG8_LDB(dst, b, h) do { _Pragma("unroll") for (int n = 0; n < 2; ++n) _Pragma("unroll") for (int k = 0; k < 2; ++k) dst[n][k] = *(const PG8_LAS bf16x8*)(lds + PG8_SB(b, h) + boff + n * 2048 + k * 1024); } while (0)
; #define PG8_MMA(ai, bj, At, Bt) do { __builtin_amdgcn_s_setprio(1); _Pragma("unroll") for (int m = 0; m < 4; ++m) _Pragma("unroll") for (int n = 0; n < 2; ++n) _Pragma("unroll") for (int k = 0; k < 2; ++k) \
;         acc[ai][bj][m][n] = __builtin_amdgcn_mfma_f32_16x16x32_bf16(Bt[n][k], At[m][k], acc[ai][bj][m][n], 0, 0, 0); __builtin_amdgcn_s_setprio(0); } while (0)
; #define PG8_WAIT_V(n) asm volatile("s_waitcnt vmcnt(" #n ")" ::: "memory")
; __device__ __forceinline__ float row_rstd(const float* ps_row) {
;     const f32x4* p = (const f32x4*)ps_row; const f32x4 a = p[0], b = p[1], c = p[2], d = p[3];
;     const float s = (sum4(a) + sum4(b)) + (sum4(c) + sum4(d));
;     return 1.0f / sqrtf(s * (1.0f / 1024.0f) + E_EPS);
; }
; template <class Epi, class Sched, bool ALIGN_EPI = false, bool SP2 = false>
; __device__ __forceinline__ void gemm_phase(PG8_LAS unsigned char* lds, const Gemm g, const Sched& S, const Epi& E) {
;     ...
;             PG8_WAIT_V(8); PG8_WAIT_L(0); PG8_BAR; PG8_MMA(0, 0, At, B0); PG8_MMA(0, 1, At, B1); PG8_BAR; PG8_SCHED;
;             PG8_LDA(At, 0, 1); PG8_STAGE(PG8_SB(0, 0), b2, voffB); PG8_STAGE(PG8_SB(0, 1), b2 + hstep, voffB); PG8_STAGE(PG8_SA(0, 0), a2, voffA);
;             PG8_WAIT_V(8); PG8_WAIT_L(0); PG8_BAR; PG8_MMA(1, 0, At, B0); PG8_MMA(1, 1, At, B1); PG8_BAR; PG8_SCHED;
;             PG8_LDB(B0, 1, 0); PG8_LDB(B1, 1, 1); PG8_SCHED; PG8_LDA(At, 1, 0); PG8_STAGE(PG8_SA(0, 1), a2 + hstep, voffA);
;             PG8_WAIT_V(8); PG8_WAIT_L(0); PG8_BAR; PG8_MMA(0, 0, At, B0); PG8_MMA(0, 1, At, B1); PG8_BAR; PG8_SCHED;
	s_setprio 1
	s_waitcnt lgkmcnt(0)
	v_mfma_f32_16x16x32_bf16 v[60:63], v[144:147], v[176:179], v[60:63]
	v_mfma_f32_16x16x32_bf16 v[52:55], v[152:155], v[176:179], v[52:55]
	v_mfma_f32_16x16x32_bf16 v[44:47], v[144:147], v[194:197], v[44:47]
	v_mfma_f32_16x16x32_bf16 v[36:39], v[152:155], v[194:197], v[36:39]
	v_mfma_f32_16x16x32_bf16 v[28:31], v[144:147], v[202:205], v[28:31]
	v_mfma_f32_16x16x32_bf16 v[20:23], v[152:155], v[202:205], v[20:23]
	v_mfma_f32_16x16x32_bf16 v[12:15], v[144:147], v[210:213], v[12:15]
	v_mfma_f32_16x16x32_bf16 v[4:7], v[152:155], v[210:213], v[4:7]
	v_mfma_f32_16x16x32_bf16 v[60:63], v[148:151], v[180:183], v[60:63]
	v_mfma_f32_16x16x32_bf16 v[52:55], v[156:159], v[180:183], v[52:55]
	v_mfma_f32_16x16x32_bf16 v[44:47], v[148:151], v[198:201], v[44:47]
	v_mfma_f32_16x16x32_bf16 v[36:39], v[156:159], v[198:201], v[36:39]
	v_mfma_f32_16x16x32_bf16 v[28:31], v[148:151], v[206:209], v[28:31]
	v_mfma_f32_16x16x32_bf16 v[20:23], v[156:159], v[206:209], v[20:23]
	v_mfma_f32_16x16x32_bf16 v[12:15], v[148:151], v[228:231], v[12:15]
	v_mfma_f32_16x16x32_bf16 v[4:7], v[156:159], v[228:231], v[4:7]
	s_setprio 0
	s_setprio 1
	v_mfma_f32_16x16x32_bf16 v[56:59], v[160:163], v[176:179], v[56:59]
	v_mfma_f32_16x16x32_bf16 v[48:51], v[168:171], v[176:179], v[48:51]
	v_mfma_f32_16x16x32_bf16 v[40:43], v[160:163], v[194:197], v[40:43]
	v_mfma_f32_16x16x32_bf16 v[32:35], v[168:171], v[194:197], v[32:35]
	v_mfma_f32_16x16x32_bf16 v[24:27], v[160:163], v[202:205], v[24:27]
	v_mfma_f32_16x16x32_bf16 v[16:19], v[168:171], v[202:205], v[16:19]
	v_mfma_f32_16x16x32_bf16 v[8:11], v[160:163], v[210:213], v[8:11]
	v_mfma_f32_16x16x32_bf16 v[0:3], v[168:171], v[210:213], v[0:3]
	v_mfma_f32_16x16x32_bf16 v[56:59], v[164:167], v[180:183], v[56:59]
	v_mfma_f32_16x16x32_bf16 v[48:51], v[172:175], v[180:183], v[48:51]
	v_mfma_f32_16x16x32_bf16 v[40:43], v[164:167], v[198:201], v[40:43]
	v_mfma_f32_16x16x32_bf16 v[32:35], v[172:175], v[198:201], v[32:35]
	v_mfma_f32_16x16x32_bf16 v[24:27], v[164:167], v[206:209], v[24:27]
	v_mfma_f32_16x16x32_bf16 v[16:19], v[172:175], v[206:209], v[16:19]
	v_mfma_f32_16x16x32_bf16 v[8:11], v[164:167], v[228:231], v[8:11]
	v_mfma_f32_16x16x32_bf16 v[0:3], v[172:175], v[228:231], v[0:3]
	s_setprio 0
	s_barrier
	s_add_i32 s52, 0, 0x18000
	s_add_i32 s53, 0, 0x1c000
	v_add_u32_e32 v156, s52, v141
	v_add_u32_e32 v172, s53, v141
	ds_read_b128 v[144:147], v156
	ds_read_b128 v[148:151], v156 offset:1024
	ds_read_b128 v[152:155], v156 offset:2048
	ds_read_b128 v[156:159], v156 offset:3072
	ds_read_b128 v[160:163], v172
	ds_read_b128 v[164:167], v172 offset:1024
	ds_read_b128 v[168:171], v172 offset:2048
	ds_read_b128 v[172:175], v172 offset:3072
	s_add_u32 s26, s26, 0x40000
	s_addc_u32 s27, s27, 0
	s_mov_b32 m0, s42
	ds_read_b128 v[176:179], v143 offset:32768
	ds_read_b128 v[180:183], v143 offset:33792
	ds_read_b128 v[194:197], v143 offset:34816
	ds_read_b128 v[198:201], v143 offset:35840
	ds_read_b128 v[202:205], v143 offset:36864
	ds_read_b128 v[206:209], v143 offset:37888
	ds_read_b128 v[210:213], v143 offset:38912
	ds_read_b128 v[228:231], v143 offset:39936
	ds_read_b128 v[232:235], v249 offset:4096
	ds_read_b128 v[136:139], v249 offset:5120
	global_load_lds_dwordx4 v134, s[26:27]
	s_mov_b32 m0, s43
	s_nop 0
	global_load_lds_dwordx4 v130, s[26:27]
	s_waitcnt vmcnt(9)
	s_waitcnt lgkmcnt(0)
	s_barrier
	s_setprio 1
	s_waitcnt lgkmcnt(0)
	v_mfma_f32_16x16x32_bf16 v[124:127], v[144:147], v[176:179], v[124:127]
	v_mfma_f32_16x16x32_bf16 v[116:119], v[152:155], v[176:179], v[116:119]
	v_mfma_f32_16x16x32_bf16 v[108:111], v[144:147], v[194:197], v[108:111]
	v_mfma_f32_16x16x32_bf16 v[100:103], v[152:155], v[194:197], v[100:103]
	v_mfma_f32_16x16x32_bf16 v[92:95], v[144:147], v[202:205], v[92:95]
	v_mfma_f32_16x16x32_bf16 v[84:87], v[152:155], v[202:205], v[84:87]
	v_mfma_f32_16x16x32_bf16 v[76:79], v[144:147], v[210:213], v[76:79]
	v_mfma_f32_16x16x32_bf16 v[68:71], v[152:155], v[210:213], v[68:71]
	v_mfma_f32_16x16x32_bf16 v[124:127], v[148:151], v[180:183], v[124:127]
	v_mfma_f32_16x16x32_bf16 v[116:119], v[156:159], v[180:183], v[116:119]
	v_mfma_f32_16x16x32_bf16 v[108:111], v[148:151], v[198:201], v[108:111]
	v_mfma_f32_16x16x32_bf16 v[100:103], v[156:159], v[198:201], v[100:103]
	v_mfma_f32_16x16x32_bf16 v[92:95], v[148:151], v[206:209], v[92:95]
	v_mfma_f32_16x16x32_bf16 v[84:87], v[156:159], v[206:209], v[84:87]
	v_mfma_f32_16x16x32_bf16 v[76:79], v[148:151], v[228:231], v[76:79]
	v_mfma_f32_16x16x32_bf16 v[68:71], v[156:159], v[228:231], v[68:71]
	s_setprio 0
	s_setprio 1
	v_mfma_f32_16x16x32_bf16 v[120:123], v[160:163], v[176:179], v[120:123]
	v_mfma_f32_16x16x32_bf16 v[112:115], v[168:171], v[176:179], v[112:115]
	v_mfma_f32_16x16x32_bf16 v[104:107], v[160:163], v[194:197], v[104:107]
	v_mfma_f32_16x16x32_bf16 v[96:99], v[168:171], v[194:197], v[96:99]
	v_mfma_f32_16x16x32_bf16 v[88:91], v[160:163], v[202:205], v[88:91]
	v_mfma_f32_16x16x32_bf16 v[80:83], v[168:171], v[202:205], v[80:83]
	v_mfma_f32_16x16x32_bf16 v[72:75], v[160:163], v[210:213], v[72:75]
	v_mfma_f32_16x16x32_bf16 v[64:67], v[168:171], v[210:213], v[64:67]
	v_mfma_f32_16x16x32_bf16 v[120:123], v[164:167], v[180:183], v[120:123]
	v_mfma_f32_16x16x32_bf16 v[112:115], v[172:175], v[180:183], v[112:115]
	v_mfma_f32_16x16x32_bf16 v[104:107], v[164:167], v[198:201], v[104:107]
	v_mfma_f32_16x16x32_bf16 v[96:99], v[172:175], v[198:201], v[96:99]
	v_mfma_f32_16x16x32_bf16 v[88:91], v[164:167], v[206:209], v[88:91]
	v_mfma_f32_16x16x32_bf16 v[80:83], v[172:175], v[206:209], v[80:83]
	v_mfma_f32_16x16x32_bf16 v[72:75], v[164:167], v[228:231], v[72:75]
	v_mfma_f32_16x16x32_bf16 v[64:67], v[172:175], v[228:231], v[64:67]
	v_mfma_f32_16x16x32_bf16 v[236:239], v[144:147], v[232:235], v[236:239]
	v_mfma_f32_16x16x32_bf16 v[240:243], v[152:155], v[232:235], v[240:243]
	v_mfma_f32_16x16x32_bf16 v[244:247], v[160:163], v[232:235], v[244:247]
	v_mfma_f32_16x16x32_bf16 v[224:227], v[168:171], v[232:235], v[224:227]
	v_mfma_f32_16x16x32_bf16 v[236:239], v[148:151], v[136:139], v[236:239]
	v_mfma_f32_16x16x32_bf16 v[240:243], v[156:159], v[136:139], v[240:243]
	v_mfma_f32_16x16x32_bf16 v[244:247], v[164:167], v[136:139], v[244:247]
	v_mfma_f32_16x16x32_bf16 v[224:227], v[172:175], v[136:139], v[224:227]
	s_setprio 0
	s_barrier
; #define PG8_LAS __attribute__((address_space(3)))
; __device__ __forceinline__ unsigned cvt_pk_bf16(float lo, float hi) { unsigned r; asm volatile("v_cvt_pk_bf16_f32 %0, %1, %2" : "=v"(r) : "v"(lo), "v"(hi)); return r; }
; __device__ __forceinline__ float sum4(const f32x4 a) { return (a[0] + a[1]) + (a[2] + a[3]); }
; #define PG8_STAGE(bufoff, gbase, voff) do { _Pragma("unroll") for (int _i = 0; _i < 2; ++_i) \
;         __builtin_amdgcn_global_load_lds((const unsigned*)((const char*)(gbase) + (voff)[_i]), (PG8_LAS unsigned*)(lds + (bufoff) + ldsw + _i * 8192), 16, 0, 0); } while (0)
; #define PG8_LDA(dst, b, h) do { _Pragma("unroll") for (int m = 0; m < 4; ++m) _Pragma("unroll") for (int k = 0; k < 2; ++k) dst[m][k] = *(const PG8_LAS bf16x8*)(lds + PG8_SA(b, h) + aoff + m * 2048 + k * 1024); } while (0)
; #define PG8_WAIT_V(n) asm volatile("s_waitcnt vmcnt(" #n ")" ::: "memory")
; __device__ __forceinline__ float row_rstd(const float* ps_row) {
;     const f32x4* p = (const f32x4*)ps_row; const f32x4 a = p[0], b = p[1], c = p[2], d = p[3];
;     const float s = (sum4(a) + sum4(b)) + (sum4(c) + sum4(d));
;     return 1.0f / sqrtf(s * (1.0f / 1024.0f) + E_EPS);
; }
; __device__ __forceinline__ u32x4 pack8(const f32x4 a, const f32x4 b) { u32x4 w; w.x = cvt_pk_bf16(a[0], a[1]); w.y = cvt_pk_bf16(a[2], a[3]); w.z = cvt_pk_bf16(b[0], b[1]); w.w = cvt_pk_bf16(b[2], b[3]); return w; }
; __device__ __forceinline__ bf16_t f2bf1(float f) { return (bf16_t)(cvt_pk_bf16(f, 0.f) & 0xffffu); }
; __device__ __forceinline__ PG8_LAS const float* stage_rstd(const float* PS, PG8_LAS unsigned char* lds, int pm) {
;     int t = threadIdx.x; asm volatile("" : "+v"(t));
;     PG8_LAS float* R = (PG8_LAS float*)(lds + 131072);
;     if (t < 256) R[t] = row_rstd(PS + (size_t)(pm * BM + t) * 16);
;     asm volatile("s_waitcnt lgkmcnt(0)" ::: "memory");
;     __builtin_amdgcn_s_barrier();
; template <class Epi, class Sched, bool ALIGN_EPI = false, bool SP2 = false>
; __device__ __forceinline__ void gemm_phase(PG8_LAS unsigned char* lds, const Gemm g, const Sched& S, const Epi& E) {
;     ...
;             PG8_LDA(At, 1, 1); PG8_STAGE(PG8_SB(1, 0), b3, voffB); PG8_STAGE(PG8_SB(1, 1), b3 + hstep, voffB); PG8_STAGE(PG8_SA(1, 0), a3, voffA);
;             PG8_WAIT_V(8); PG8_WAIT_L(0); PG8_BAR; PG8_MMA(1, 0, At, B0); PG8_MMA(1, 1, At, B1); PG8_BAR; PG8_SCHED;
	s_add_i32 s52, s52, s39
	s_add_u32 s98, s24, 0x80
	s_addc_u32 s99, s25, 0
	s_mov_b32 m0, s52
	ds_read_b128 v[176:179], v143 offset:49152
	ds_read_b128 v[180:183], v143 offset:50176
	ds_read_b128 v[194:197], v143 offset:51200
	ds_read_b128 v[198:201], v143 offset:52224
	ds_read_b128 v[202:205], v143 offset:53248
	ds_read_b128 v[206:209], v143 offset:54272
	ds_read_b128 v[210:213], v143 offset:55296
	ds_read_b128 v[228:231], v143 offset:56320
	global_load_lds_dwordx4 v132, s[98:99]
	s_add_i32 m0, s52, 0x2000
	s_add_u32 s100, s26, 0xfffc0080
	s_addc_u32 s101, s27, -1
	s_add_i32 s53, s53, s39
	global_load_lds_dwordx4 v128, s[98:99]
	s_add_u32 s98, s98, 0x40000
	s_addc_u32 s99, s99, 0
	s_mov_b32 m0, s53
	s_nop 0
	global_load_lds_dwordx4 v132, s[98:99]
	s_add_i32 m0, s53, 0x2000
	s_nop 0
	global_load_lds_dwordx4 v128, s[98:99]
	s_mov_b32 m0, s44
	s_nop 0
	global_load_lds_dwordx4 v134, s[100:101]
	s_mov_b32 m0, s45
	s_nop 0
	global_load_lds_dwordx4 v130, s[100:101]
	s_and_b32 m0, s39, 0xc00
	s_add_i32 m0, m0, 0x21800
	s_nop 0
	global_load_lds_dwordx4 v248, s[100:101]
	s_waitcnt vmcnt(9)
	s_waitcnt lgkmcnt(0)
	s_barrier
	s_setprio 1
	s_waitcnt lgkmcnt(0)
	v_mfma_f32_16x16x32_bf16 v[60:63], v[144:147], v[176:179], v[60:63]
	v_mfma_f32_16x16x32_bf16 v[52:55], v[152:155], v[176:179], v[52:55]
	v_mfma_f32_16x16x32_bf16 v[44:47], v[144:147], v[194:197], v[44:47]
	v_mfma_f32_16x16x32_bf16 v[36:39], v[152:155], v[194:197], v[36:39]
	v_mfma_f32_16x16x32_bf16 v[28:31], v[144:147], v[202:205], v[28:31]
	v_mfma_f32_16x16x32_bf16 v[20:23], v[152:155], v[202:205], v[20:23]
	v_mfma_f32_16x16x32_bf16 v[12:15], v[144:147], v[210:213], v[12:15]
	v_mfma_f32_16x16x32_bf16 v[4:7], v[152:155], v[210:213], v[4:7]
	v_mfma_f32_16x16x32_bf16 v[60:63], v[148:151], v[180:183], v[60:63]
	v_mfma_f32_16x16x32_bf16 v[52:55], v[156:159], v[180:183], v[52:55]
	v_mfma_f32_16x16x32_bf16 v[44:47], v[148:151], v[198:201], v[44:47]
	v_mfma_f32_16x16x32_bf16 v[36:39], v[156:159], v[198:201], v[36:39]
	v_mfma_f32_16x16x32_bf16 v[28:31], v[148:151], v[206:209], v[28:31]
	v_mfma_f32_16x16x32_bf16 v[20:23], v[156:159], v[206:209], v[20:23]
	v_mfma_f32_16x16x32_bf16 v[12:15], v[148:151], v[228:231], v[12:15]
	v_mfma_f32_16x16x32_bf16 v[4:7], v[156:159], v[228:231], v[4:7]
	s_setprio 0
	s_setprio 1
	v_mfma_f32_16x16x32_bf16 v[56:59], v[160:163], v[176:179], v[56:59]
	v_mfma_f32_16x16x32_bf16 v[48:51], v[168:171], v[176:179], v[48:51]
	v_mfma_f32_16x16x32_bf16 v[40:43], v[160:163], v[194:197], v[40:43]
	v_mfma_f32_16x16x32_bf16 v[32:35], v[168:171], v[194:197], v[32:35]
	v_mfma_f32_16x16x32_bf16 v[24:27], v[160:163], v[202:205], v[24:27]
	v_mfma_f32_16x16x32_bf16 v[16:19], v[168:171], v[202:205], v[16:19]
	v_mfma_f32_16x16x32_bf16 v[8:11], v[160:163], v[210:213], v[8:11]
	v_mfma_f32_16x16x32_bf16 v[0:3], v[168:171], v[210:213], v[0:3]
	v_mfma_f32_16x16x32_bf16 v[56:59], v[164:167], v[180:183], v[56:59]
	v_mfma_f32_16x16x32_bf16 v[48:51], v[172:175], v[180:183], v[48:51]
	v_mfma_f32_16x16x32_bf16 v[40:43], v[164:167], v[198:201], v[40:43]
	v_mfma_f32_16x16x32_bf16 v[32:35], v[172:175], v[198:201], v[32:35]
	v_mfma_f32_16x16x32_bf16 v[24:27], v[164:167], v[206:209], v[24:27]
	v_mfma_f32_16x16x32_bf16 v[16:19], v[172:175], v[206:209], v[16:19]
	v_mfma_f32_16x16x32_bf16 v[8:11], v[164:167], v[228:231], v[8:11]
	v_mfma_f32_16x16x32_bf16 v[0:3], v[172:175], v[228:231], v[0:3]
	s_setprio 0
	s_barrier
	s_add_i32 s51, s51, 2
	s_add_u32 s0, s0, 0x100
	s_addc_u32 s1, s1, 0
	s_add_u32 s49, s49, 0x100
	s_addc_u32 s50, s50, 0
	s_cmp_gt_u32 s51, 13
	s_cbranch_scc0 .LBB0_35
	s_and_b64 vcc, exec, s[12:13]
	s_cbranch_vccz .LBB0_38
	s_barrier
.LBB0_38:
	v_mov_b32_e32 v144, v216
	s_movk_i32 s0, 0x120
	s_mul_i32 s3, s48, 0x120
	v_cmp_gt_i32_e32 vcc, s0, v144
	s_and_saveexec_b64 s[24:25], vcc
	s_cbranch_execz .LBB0_40
	v_add_u32_e32 v146, s3, v144
	v_ashrrev_i32_e32 v147, 31, v146
	v_lshlrev_b64 v[146:147], 6, v[146:147]
	v_lshl_add_u64 v[158:159], s[14:15], 0, v[146:147]
	global_load_dwordx4 v[146:149], v[158:159], off
	global_load_dwordx4 v[150:153], v[158:159], off offset:32
	global_load_dwordx4 v[154:157], v[158:159], off offset:16
	s_nop 0
	global_load_dwordx4 v[158:161], v[158:159], off offset:48
	s_mov_b32 s0, 0xf800000
	v_lshl_add_u32 v144, v144, 2, 0
	v_add_u32_e32 v144, 0x20000, v144
	s_waitcnt vmcnt(0)
	v_mov_b32_e32 v162, v146
	v_mov_b32_e32 v163, v150
	v_mov_b32_e32 v150, v147
	v_mov_b32_e32 v146, v148
	v_mov_b32_e32 v147, v152
	v_mov_b32_e32 v152, v149
	v_mov_b32_e32 v148, v154
	v_mov_b32_e32 v149, v158
	v_mov_b32_e32 v158, v155
	v_mov_b32_e32 v154, v156
	v_mov_b32_e32 v155, v160
	v_mov_b32_e32 v160, v157
	v_pk_add_f32 v[150:151], v[162:163], v[150:151]
	v_pk_add_f32 v[146:147], v[146:147], v[152:153]
	v_pk_add_f32 v[148:149], v[148:149], v[158:159]
	v_pk_add_f32 v[152:153], v[154:155], v[160:161]
	v_pk_add_f32 v[146:147], v[150:151], v[146:147]
	v_pk_add_f32 v[148:149], v[148:149], v[152:153]
	s_nop 0
	v_pk_add_f32 v[146:147], v[146:147], v[148:149]
	s_nop 0
	v_add_f32_e32 v145, v146, v147
	v_fmamk_f32 v145, v145, 0x3a800000, v218
	v_mul_f32_e32 v146, 0x4f800000, v145
	v_cmp_gt_f32_e32 vcc, s0, v145
	s_nop 1
	v_cndmask_b32_e32 v145, v145, v146, vcc
	v_sqrt_f32_e32 v146, v145
	s_nop 0
	v_add_u32_e32 v147, -1, v146
	v_add_u32_e32 v148, 1, v146
	v_fma_f32 v149, -v147, v146, v145
	v_fma_f32 v150, -v148, v146, v145
	v_cmp_ge_f32_e64 s[0:1], 0, v149
	s_nop 1
	v_cndmask_b32_e64 v146, v146, v147, s[0:1]
	v_cmp_lt_f32_e64 s[0:1], 0, v150
	s_nop 1
	v_cndmask_b32_e64 v146, v146, v148, s[0:1]
	v_mul_f32_e32 v147, 0x37800000, v146
	v_cndmask_b32_e32 v146, v146, v147, vcc
	v_cmp_class_f32_e32 vcc, v145, v219
	s_nop 1
	v_cndmask_b32_e32 v145, v146, v145, vcc
	v_div_scale_f32 v146, s[0:1], v145, v145, 1.0
	v_rcp_f32_e32 v147, v146
	v_div_scale_f32 v148, vcc, 1.0, v145, 1.0
	v_fma_f32 v149, -v146, v147, 1.0
	v_fmac_f32_e32 v147, v149, v147
	v_mul_f32_e32 v149, v148, v147
	v_fma_f32 v150, -v146, v149, v148
	v_fmac_f32_e32 v149, v150, v147
	v_fma_f32 v146, -v146, v149, v148
	v_div_fmas_f32 v146, v146, v147, v149
	v_div_fixup_f32 v145, v146, v145, 1.0
	ds_write_b32 v144, v145
; #define PG8_LAS __attribute__((address_space(3)))
; __device__ __forceinline__ u32x4 pack8(const f32x4 a, const f32x4 b) { u32x4 w; w.x = cvt_pk_bf16(a[0], a[1]); w.y = cvt_pk_bf16(a[2], a[3]); w.z = cvt_pk_bf16(b[0], b[1]); w.w = cvt_pk_bf16(b[2], b[3]); return w; }
;     __device__ __forceinline__ void operator()(const f32x4 (&acc)[2][2][4][2], const Unit& u, int wr, int wc, int fr, int fq) const {
;         PG8_LAS const float* R = stage_rstd((const float*)(ws + WS_PS), lds, u.pm);
; #pragma unroll
;         for (int ai = 0; ai < 2; ++ai)
; #pragma unroll
;             for (int m = 0; m < 4; ++m) {
;                 const int row = u.pm * BM + ai * HALF + wr * 64 + m * 16 + fr;
;                 const float rs = R[ai * HALF + wr * 64 + m * 16 + fr];
;                 bf16_t* ACT = (bf16_t*)(ws + WS_ACT);
;                 f32x4 a[2];
; #pragma unroll
;                 for (int n = 0; n < 2; ++n) {
;                     const f32x4 g = acc[ai][0][m][n] * rs, uu = acc[ai][1][m][n] * rs;
; #pragma unroll
;                     for (int j = 0; j < 4; ++j) a[n][j] = g[j] * __builtin_amdgcn_rcpf(1.0f + __builtin_amdgcn_exp2f(-1.4426950408889634f * g[j])) * uu[j];
;                 }
;                 *(u32x4*)(ACT + (size_t)row * 2816 + u.pn * 128 + wc * 32 + 8 * fq) = pack8(a[0], a[1]);
;             }
.LBB0_40:
	s_or_b64 exec, exec, s[24:25]
	s_waitcnt lgkmcnt(0)
	s_barrier
	v_and_b32_e32 v144, 15, v216
	s_lshr_b32 s98, s39, 12
	s_lshl_b32 s98, s98, 4
	v_add_u32_e32 v144, s98, v144
	v_lshlrev_b32_e32 v145, 2, v144
	v_add_u32_e32 v145, 0x20400, v145
	ds_read_b32 v146, v145
	v_add_u32_e32 v147, s3, v144
	v_add_u32_e32 v147, 0x100, v147
	v_mov_b64_e32 v[148:149], s[16:17]
	s_movk_i32 s100, 0x1600
	v_mad_i64_i32 v[150:151], vcc, v147, s100, v[148:149]
	s_lshl_b32 s98, s47, 8
	s_add_i32 s98, s98, s34
	s_mov_b32 s99, 0
	v_lshl_add_u64 v[150:151], v[150:151], 0, s[98:99]
	v_lshl_add_u64 v[150:151], v[150:151], 0, v[184:185]
	s_waitcnt lgkmcnt(0)
	v_mul_f32_e32 v156, v236, v146
	v_mul_f32_e32 v160, v244, v146
	v_mul_f32_e32 v157, v237, v146
	v_mul_f32_e32 v161, v245, v146
	v_mul_f32_e32 v158, v238, v146
	v_mul_f32_e32 v162, v246, v146
	v_mul_f32_e32 v159, v239, v146
	v_mul_f32_e32 v163, v247, v146
	v_mul_f32_e32 v172, 0xbfb8aa3b, v156
	v_mul_f32_e32 v173, 0xbfb8aa3b, v157
	v_mul_f32_e32 v174, 0xbfb8aa3b, v158
	v_mul_f32_e32 v175, 0xbfb8aa3b, v159
	v_exp_f32_e32 v172, v172
	v_exp_f32_e32 v173, v173
	v_exp_f32_e32 v174, v174
	v_exp_f32_e32 v175, v175
	s_nop 0
	v_add_f32_e32 v172, 1.0, v172
	v_add_f32_e32 v173, 1.0, v173
	v_add_f32_e32 v174, 1.0, v174
	v_add_f32_e32 v175, 1.0, v175
	v_rcp_f32_e32 v172, v172
	v_rcp_f32_e32 v173, v173
	v_rcp_f32_e32 v174, v174
	v_rcp_f32_e32 v175, v175
	s_nop 0
	v_mul_f32_e32 v172, v156, v172
	v_mul_f32_e32 v173, v157, v173
	v_mul_f32_e32 v174, v158, v174
	v_mul_f32_e32 v175, v159, v175
	v_mul_f32_e32 v164, v160, v172
	v_mul_f32_e32 v165, v161, v173
	v_mul_f32_e32 v166, v162, v174
	v_mul_f32_e32 v167, v163, v175
	v_mul_f32_e32 v156, v240, v146
	v_mul_f32_e32 v160, v224, v146
	v_mul_f32_e32 v157, v241, v146
	v_mul_f32_e32 v161, v225, v146
	v_mul_f32_e32 v158, v242, v146
	v_mul_f32_e32 v162, v226, v146
	v_mul_f32_e32 v159, v243, v146
	v_mul_f32_e32 v163, v227, v146
	v_mul_f32_e32 v172, 0xbfb8aa3b, v156
	v_mul_f32_e32 v173, 0xbfb8aa3b, v157
	v_mul_f32_e32 v174, 0xbfb8aa3b, v158
	v_mul_f32_e32 v175, 0xbfb8aa3b, v159
	v_exp_f32_e32 v172, v172
	v_exp_f32_e32 v173, v173
	v_exp_f32_e32 v174, v174
	v_exp_f32_e32 v175, v175
	s_nop 0
	v_add_f32_e32 v172, 1.0, v172
	v_add_f32_e32 v173, 1.0, v173
	v_add_f32_e32 v174, 1.0, v174
	v_add_f32_e32 v175, 1.0, v175
	v_rcp_f32_e32 v172, v172
	v_rcp_f32_e32 v173, v173
	v_rcp_f32_e32 v174, v174
	v_rcp_f32_e32 v175, v175
	s_nop 0
	v_mul_f32_e32 v172, v156, v172
	v_mul_f32_e32 v173, v157, v173
	v_mul_f32_e32 v174, v158, v174
	v_mul_f32_e32 v175, v159, v175
	v_mul_f32_e32 v168, v160, v172
	v_mul_f32_e32 v169, v161, v173
	v_mul_f32_e32 v170, v162, v174
	v_mul_f32_e32 v171, v163, v175
	v_cvt_pk_bf16_f32 v152, v164, v165
	v_cvt_pk_bf16_f32 v153, v166, v167
	v_cvt_pk_bf16_f32 v154, v168, v169
	v_cvt_pk_bf16_f32 v155, v170, v171
	global_store_dwordx4 v[150:151], v[152:155], off
	ds_read_b32 v146, v142
	v_mov_b32_e32 v148, v120
	v_mov_b32_e32 v149, v124
	v_mov_b32_e32 v124, v121
	s_lshl_b32 s0, s47, 7
	s_waitcnt lgkmcnt(0)
	v_pk_mul_f32 v[148:149], v[148:149], v[146:147] op_sel_hi:[1,0]
	v_add_u32_e32 v144, s3, v140
	v_mul_f32_e32 v120, 0xbfb8aa3b, v149
	v_exp_f32_e32 v120, v120
	s_ashr_i32 s1, s0, 31
	s_movk_i32 s3, 0x1600
	s_lshl_b64 s[0:1], s[0:1], 1
	v_add_f32_e32 v120, 1.0, v120
	v_rcp_f32_e32 v120, v120
	s_andn2_b64 vcc, exec, s[36:37]
	v_mul_f32_e32 v120, v149, v120
	v_mul_f32_e32 v145, v148, v120
	v_pk_mul_f32 v[120:121], v[124:125], v[146:147] op_sel_hi:[1,0]
	s_nop 0
	v_mul_f32_e32 v124, 0xbfb8aa3b, v121
	v_exp_f32_e32 v124, v124
	s_nop 0
	v_add_f32_e32 v124, 1.0, v124
	v_rcp_f32_e32 v124, v124
	s_nop 0
	v_mul_f32_e32 v121, v121, v124
	v_mul_f32_e32 v124, v120, v121
	v_mov_b32_e32 v120, v122
	v_mov_b32_e32 v121, v126
	v_pk_mul_f32 v[120:121], v[120:121], v[146:147] op_sel_hi:[1,0]
	v_mov_b32_e32 v126, v123
	v_mul_f32_e32 v122, 0xbfb8aa3b, v121
	v_exp_f32_e32 v122, v122
	s_nop 0
	v_add_f32_e32 v122, 1.0, v122
	v_rcp_f32_e32 v122, v122
	s_nop 0
	v_mul_f32_e32 v121, v121, v122
	v_mul_f32_e32 v122, v120, v121
	v_pk_mul_f32 v[120:121], v[126:127], v[146:147] op_sel_hi:[1,0]
	s_nop 0
	v_mul_f32_e32 v123, 0xbfb8aa3b, v121
	v_exp_f32_e32 v123, v123
	s_nop 0
	v_add_f32_e32 v123, 1.0, v123
	v_rcp_f32_e32 v123, v123
	s_nop 0
	v_mul_f32_e32 v121, v121, v123
	v_mul_f32_e32 v123, v120, v121
	v_mov_b32_e32 v120, v112
	v_mov_b32_e32 v121, v116
	v_pk_mul_f32 v[120:121], v[120:121], v[146:147] op_sel_hi:[1,0]
	v_mov_b32_e32 v116, v113
	v_mul_f32_e32 v112, 0xbfb8aa3b, v121
	v_exp_f32_e32 v112, v112
	s_nop 0
	v_add_f32_e32 v112, 1.0, v112
	v_rcp_f32_e32 v112, v112
	s_nop 0
	v_mul_f32_e32 v112, v121, v112
	v_mul_f32_e32 v120, v120, v112
	v_pk_mul_f32 v[112:113], v[116:117], v[146:147] op_sel_hi:[1,0]
	s_nop 0
	v_mul_f32_e32 v116, 0xbfb8aa3b, v113
	v_exp_f32_e32 v116, v116
	s_nop 0
	v_add_f32_e32 v116, 1.0, v116
	v_rcp_f32_e32 v116, v116
	s_nop 0
	v_mul_f32_e32 v113, v113, v116
	v_mul_f32_e32 v116, v112, v113
	v_mov_b32_e32 v112, v114
	v_mov_b32_e32 v113, v118
	v_pk_mul_f32 v[112:113], v[112:113], v[146:147] op_sel_hi:[1,0]
	v_mov_b32_e32 v118, v115
	v_mul_f32_e32 v114, 0xbfb8aa3b, v113
	v_exp_f32_e32 v114, v114
	s_nop 0
	v_add_f32_e32 v114, 1.0, v114
	v_rcp_f32_e32 v114, v114
	s_nop 0
	v_mul_f32_e32 v113, v113, v114
	v_mul_f32_e32 v117, v112, v113
	v_pk_mul_f32 v[112:113], v[118:119], v[146:147] op_sel_hi:[1,0]
	s_nop 0
	v_mul_f32_e32 v114, 0xbfb8aa3b, v113
	v_exp_f32_e32 v114, v114
	s_nop 0
	v_add_f32_e32 v114, 1.0, v114
	v_rcp_f32_e32 v114, v114
	s_nop 0
	v_mul_f32_e32 v113, v113, v114
	v_mul_f32_e32 v112, v112, v113
	v_cvt_pk_bf16_f32 v114, v145, v124
	v_cvt_pk_bf16_f32 v115, v122, v123
	v_cvt_pk_bf16_f32 v116, v120, v116
	v_cvt_pk_bf16_f32 v117, v117, v112
	v_mov_b64_e32 v[112:113], s[16:17]
	v_mad_i64_i32 v[118:119], s[4:5], v144, s3, v[112:113]
	v_lshl_add_u64 v[118:119], v[118:119], 0, s[0:1]
	v_lshl_add_u64 v[118:119], v[118:119], 0, s[34:35]
	v_lshl_add_u64 v[118:119], v[118:119], 0, v[184:185]
	global_store_dwordx4 v[118:119], v[114:117], off
	ds_read_b32 v114, v142 offset:64
	s_nop 0
	v_mov_b32_e32 v116, v104
	v_mov_b32_e32 v117, v108
	v_mov_b32_e32 v108, v105
	s_waitcnt lgkmcnt(0)
; __device__ __forceinline__ u32x4 pack8(const f32x4 a, const f32x4 b) { u32x4 w; w.x = cvt_pk_bf16(a[0], a[1]); w.y = cvt_pk_bf16(a[2], a[3]); w.z = cvt_pk_bf16(b[0], b[1]); w.w = cvt_pk_bf16(b[2], b[3]); return w; }
;     __device__ __forceinline__ void operator()(const f32x4 (&acc)[2][2][4][2], const Unit& u, int wr, int wc, int fr, int fq) const {
;     ...
;         for (int ai = 0; ai < 2; ++ai)
; #pragma unroll
;             for (int m = 0; m < 4; ++m) {
;                 const int row = u.pm * BM + ai * HALF + wr * 64 + m * 16 + fr;
;                 const float rs = R[ai * HALF + wr * 64 + m * 16 + fr];
;                 bf16_t* ACT = (bf16_t*)(ws + WS_ACT);
;                 f32x4 a[2];
; #pragma unroll
;                 for (int n = 0; n < 2; ++n) {
;                     const f32x4 g = acc[ai][0][m][n] * rs, uu = acc[ai][1][m][n] * rs;
; #pragma unroll
;                     for (int j = 0; j < 4; ++j) a[n][j] = g[j] * __builtin_amdgcn_rcpf(1.0f + __builtin_amdgcn_exp2f(-1.4426950408889634f * g[j])) * uu[j];
;                 }
;                 *(u32x4*)(ACT + (size_t)row * 2816 + u.pn * 128 + wc * 32 + 8 * fq) = pack8(a[0], a[1]);
;             }
	v_pk_mul_f32 v[116:117], v[116:117], v[114:115] op_sel_hi:[1,0]
	s_nop 0
	v_mul_f32_e32 v104, 0xbfb8aa3b, v117
	v_exp_f32_e32 v104, v104
	s_nop 0
	v_add_f32_e32 v104, 1.0, v104
	v_rcp_f32_e32 v104, v104
	s_nop 0
	v_mul_f32_e32 v104, v117, v104
	v_mul_f32_e32 v115, v116, v104
	v_pk_mul_f32 v[104:105], v[108:109], v[114:115] op_sel_hi:[1,0]
	s_nop 0
	v_mul_f32_e32 v108, 0xbfb8aa3b, v105
	v_exp_f32_e32 v108, v108
	s_nop 0
	v_add_f32_e32 v108, 1.0, v108
	v_rcp_f32_e32 v108, v108
	s_nop 0
	v_mul_f32_e32 v105, v105, v108
	v_mul_f32_e32 v108, v104, v105
	v_mov_b32_e32 v104, v106
	v_mov_b32_e32 v105, v110
	v_pk_mul_f32 v[104:105], v[104:105], v[114:115] op_sel_hi:[1,0]
	v_mov_b32_e32 v110, v107
	v_mul_f32_e32 v106, 0xbfb8aa3b, v105
	v_exp_f32_e32 v106, v106
	s_nop 0
	v_add_f32_e32 v106, 1.0, v106
	v_rcp_f32_e32 v106, v106
	s_nop 0
	v_mul_f32_e32 v105, v105, v106
	v_mul_f32_e32 v106, v104, v105
	v_pk_mul_f32 v[104:105], v[110:111], v[114:115] op_sel_hi:[1,0]
	s_nop 0
	v_mul_f32_e32 v107, 0xbfb8aa3b, v105
	v_exp_f32_e32 v107, v107
	s_nop 0
	v_add_f32_e32 v107, 1.0, v107
	v_rcp_f32_e32 v107, v107
	s_nop 0
	v_mul_f32_e32 v105, v105, v107
	v_mul_f32_e32 v107, v104, v105
	v_mov_b32_e32 v104, v96
	v_mov_b32_e32 v105, v100
	v_pk_mul_f32 v[104:105], v[104:105], v[114:115] op_sel_hi:[1,0]
	v_mov_b32_e32 v100, v97
	v_mul_f32_e32 v96, 0xbfb8aa3b, v105
	v_exp_f32_e32 v96, v96
	s_nop 0
	v_add_f32_e32 v96, 1.0, v96
	v_rcp_f32_e32 v96, v96
	s_nop 0
	v_mul_f32_e32 v96, v105, v96
	v_mul_f32_e32 v104, v104, v96
	v_pk_mul_f32 v[96:97], v[100:101], v[114:115] op_sel_hi:[1,0]
	s_nop 0
	v_mul_f32_e32 v100, 0xbfb8aa3b, v97
	v_exp_f32_e32 v100, v100
	s_nop 0
	v_add_f32_e32 v100, 1.0, v100
	v_rcp_f32_e32 v100, v100
	s_nop 0
	v_mul_f32_e32 v97, v97, v100
	v_mul_f32_e32 v100, v96, v97
	v_mov_b32_e32 v96, v98
	v_mov_b32_e32 v97, v102
	v_pk_mul_f32 v[96:97], v[96:97], v[114:115] op_sel_hi:[1,0]
	v_mov_b32_e32 v102, v99
	v_mul_f32_e32 v98, 0xbfb8aa3b, v97
	v_exp_f32_e32 v98, v98
	s_nop 0
	v_add_f32_e32 v98, 1.0, v98
	v_rcp_f32_e32 v98, v98
	s_nop 0
	v_mul_f32_e32 v97, v97, v98
	v_mul_f32_e32 v101, v96, v97
	v_pk_mul_f32 v[96:97], v[102:103], v[114:115] op_sel_hi:[1,0]
	v_add_u32_e32 v102, 16, v144
	v_mul_f32_e32 v98, 0xbfb8aa3b, v97
	v_exp_f32_e32 v98, v98
	s_nop 0
	v_add_f32_e32 v98, 1.0, v98
	v_rcp_f32_e32 v98, v98
	s_nop 0
	v_mul_f32_e32 v97, v97, v98
	v_mul_f32_e32 v99, v96, v97
	v_cvt_pk_bf16_f32 v96, v115, v108
	v_cvt_pk_bf16_f32 v97, v106, v107
	v_cvt_pk_bf16_f32 v98, v104, v100
	v_cvt_pk_bf16_f32 v99, v101, v99
	v_mad_i64_i32 v[100:101], s[4:5], v102, s3, v[112:113]
	v_lshl_add_u64 v[100:101], v[100:101], 0, s[0:1]
	v_lshl_add_u64 v[100:101], v[100:101], 0, s[34:35]
	v_lshl_add_u64 v[100:101], v[100:101], 0, v[184:185]
	global_store_dwordx4 v[100:101], v[96:99], off
	ds_read_b32 v96, v142 offset:128
	s_nop 0
	v_mov_b32_e32 v98, v88
	v_mov_b32_e32 v99, v92
	v_mov_b32_e32 v92, v89
	s_waitcnt lgkmcnt(0)
	v_pk_mul_f32 v[98:99], v[98:99], v[96:97] op_sel_hi:[1,0]
	s_nop 0
	v_mul_f32_e32 v88, 0xbfb8aa3b, v99
	v_exp_f32_e32 v88, v88
	s_nop 0
	v_add_f32_e32 v88, 1.0, v88
	v_rcp_f32_e32 v88, v88
	s_nop 0
	v_mul_f32_e32 v88, v99, v88
	v_mul_f32_e32 v97, v98, v88
	v_pk_mul_f32 v[88:89], v[92:93], v[96:97] op_sel_hi:[1,0]
	s_nop 0
	v_mul_f32_e32 v92, 0xbfb8aa3b, v89
	v_exp_f32_e32 v92, v92
	s_nop 0
	v_add_f32_e32 v92, 1.0, v92
	v_rcp_f32_e32 v92, v92
	s_nop 0
	v_mul_f32_e32 v89, v89, v92
	v_mul_f32_e32 v92, v88, v89
	v_mov_b32_e32 v88, v90
	v_mov_b32_e32 v89, v94
	v_pk_mul_f32 v[88:89], v[88:89], v[96:97] op_sel_hi:[1,0]
	v_mov_b32_e32 v94, v91
	v_mul_f32_e32 v90, 0xbfb8aa3b, v89
	v_exp_f32_e32 v90, v90
	s_nop 0
	v_add_f32_e32 v90, 1.0, v90
	v_rcp_f32_e32 v90, v90
	s_nop 0
	v_mul_f32_e32 v89, v89, v90
	v_mul_f32_e32 v90, v88, v89
	v_pk_mul_f32 v[88:89], v[94:95], v[96:97] op_sel_hi:[1,0]
	s_nop 0
	v_mul_f32_e32 v91, 0xbfb8aa3b, v89
	v_exp_f32_e32 v91, v91
	s_nop 0
	v_add_f32_e32 v91, 1.0, v91
	v_rcp_f32_e32 v91, v91
	s_nop 0
	v_mul_f32_e32 v89, v89, v91
	v_mul_f32_e32 v91, v88, v89
	v_mov_b32_e32 v88, v80
	v_mov_b32_e32 v89, v84
	v_pk_mul_f32 v[88:89], v[88:89], v[96:97] op_sel_hi:[1,0]
	v_mov_b32_e32 v84, v81
	v_mul_f32_e32 v80, 0xbfb8aa3b, v89
	v_exp_f32_e32 v80, v80
	s_nop 0
	v_add_f32_e32 v80, 1.0, v80
	v_rcp_f32_e32 v80, v80
	s_nop 0
	v_mul_f32_e32 v80, v89, v80
	v_mul_f32_e32 v88, v88, v80
	v_pk_mul_f32 v[80:81], v[84:85], v[96:97] op_sel_hi:[1,0]
	s_nop 0
	v_mul_f32_e32 v84, 0xbfb8aa3b, v81
	v_exp_f32_e32 v84, v84
	s_nop 0
	v_add_f32_e32 v84, 1.0, v84
	v_rcp_f32_e32 v84, v84
	s_nop 0
	v_mul_f32_e32 v81, v81, v84
	v_mul_f32_e32 v84, v80, v81
	v_mov_b32_e32 v80, v82
	v_mov_b32_e32 v81, v86
	v_pk_mul_f32 v[80:81], v[80:81], v[96:97] op_sel_hi:[1,0]
	v_mov_b32_e32 v86, v83
	v_mul_f32_e32 v82, 0xbfb8aa3b, v81
	v_exp_f32_e32 v82, v82
	s_nop 0
	v_add_f32_e32 v82, 1.0, v82
	v_rcp_f32_e32 v82, v82
	s_nop 0
	v_mul_f32_e32 v81, v81, v82
	v_mul_f32_e32 v85, v80, v81
	v_pk_mul_f32 v[80:81], v[86:87], v[96:97] op_sel_hi:[1,0]
	v_add_u32_e32 v86, 32, v144
	v_mul_f32_e32 v82, 0xbfb8aa3b, v81
	v_exp_f32_e32 v82, v82
	s_nop 0
	v_add_f32_e32 v82, 1.0, v82
	v_rcp_f32_e32 v82, v82
	s_nop 0
	v_mul_f32_e32 v81, v81, v82
	v_mul_f32_e32 v83, v80, v81
	v_cvt_pk_bf16_f32 v80, v97, v92
	v_cvt_pk_bf16_f32 v81, v90, v91
	v_cvt_pk_bf16_f32 v82, v88, v84
	v_cvt_pk_bf16_f32 v83, v85, v83
	v_mad_i64_i32 v[84:85], s[4:5], v86, s3, v[112:113]
	v_lshl_add_u64 v[84:85], v[84:85], 0, s[0:1]
	v_lshl_add_u64 v[84:85], v[84:85], 0, s[34:35]
	v_lshl_add_u64 v[84:85], v[84:85], 0, v[184:185]
	global_store_dwordx4 v[84:85], v[80:83], off
	ds_read_b32 v80, v142 offset:192
	s_nop 0
	v_mov_b32_e32 v82, v72
	v_mov_b32_e32 v83, v76
	v_mov_b32_e32 v76, v73
	s_waitcnt lgkmcnt(0)
; __device__ __forceinline__ u32x4 pack8(const f32x4 a, const f32x4 b) { u32x4 w; w.x = cvt_pk_bf16(a[0], a[1]); w.y = cvt_pk_bf16(a[2], a[3]); w.z = cvt_pk_bf16(b[0], b[1]); w.w = cvt_pk_bf16(b[2], b[3]); return w; }
;     __device__ __forceinline__ void operator()(const f32x4 (&acc)[2][2][4][2], const Unit& u, int wr, int wc, int fr, int fq) const {
;     ...
;         for (int ai = 0; ai < 2; ++ai)
; #pragma unroll
;             for (int m = 0; m < 4; ++m) {
;                 const int row = u.pm * BM + ai * HALF + wr * 64 + m * 16 + fr;
;                 const float rs = R[ai * HALF + wr * 64 + m * 16 + fr];
;                 bf16_t* ACT = (bf16_t*)(ws + WS_ACT);
;                 f32x4 a[2];
; #pragma unroll
;                 for (int n = 0; n < 2; ++n) {
;                     const f32x4 g = acc[ai][0][m][n] * rs, uu = acc[ai][1][m][n] * rs;
; #pragma unroll
;                     for (int j = 0; j < 4; ++j) a[n][j] = g[j] * __builtin_amdgcn_rcpf(1.0f + __builtin_amdgcn_exp2f(-1.4426950408889634f * g[j])) * uu[j];
;                 }
;                 *(u32x4*)(ACT + (size_t)row * 2816 + u.pn * 128 + wc * 32 + 8 * fq) = pack8(a[0], a[1]);
;             }
	v_pk_mul_f32 v[82:83], v[82:83], v[80:81] op_sel_hi:[1,0]
	s_nop 0
	v_mul_f32_e32 v72, 0xbfb8aa3b, v83
	v_exp_f32_e32 v72, v72
	s_nop 0
	v_add_f32_e32 v72, 1.0, v72
	v_rcp_f32_e32 v72, v72
	s_nop 0
	v_mul_f32_e32 v72, v83, v72
	v_mul_f32_e32 v81, v82, v72
	v_pk_mul_f32 v[72:73], v[76:77], v[80:81] op_sel_hi:[1,0]
	s_nop 0
	v_mul_f32_e32 v76, 0xbfb8aa3b, v73
	v_exp_f32_e32 v76, v76
	s_nop 0
	v_add_f32_e32 v76, 1.0, v76
	v_rcp_f32_e32 v76, v76
	s_nop 0
	v_mul_f32_e32 v73, v73, v76
	v_mul_f32_e32 v76, v72, v73
	v_mov_b32_e32 v72, v74
	v_mov_b32_e32 v73, v78
	v_pk_mul_f32 v[72:73], v[72:73], v[80:81] op_sel_hi:[1,0]
	v_mov_b32_e32 v78, v75
	v_mul_f32_e32 v74, 0xbfb8aa3b, v73
	v_exp_f32_e32 v74, v74
	s_nop 0
	v_add_f32_e32 v74, 1.0, v74
	v_rcp_f32_e32 v74, v74
	s_nop 0
	v_mul_f32_e32 v73, v73, v74
	v_mul_f32_e32 v74, v72, v73
	v_pk_mul_f32 v[72:73], v[78:79], v[80:81] op_sel_hi:[1,0]
	s_nop 0
	v_mul_f32_e32 v75, 0xbfb8aa3b, v73
	v_exp_f32_e32 v75, v75
	s_nop 0
	v_add_f32_e32 v75, 1.0, v75
	v_rcp_f32_e32 v75, v75
	s_nop 0
	v_mul_f32_e32 v73, v73, v75
	v_mul_f32_e32 v75, v72, v73
	v_mov_b32_e32 v72, v64
	v_mov_b32_e32 v73, v68
	v_pk_mul_f32 v[72:73], v[72:73], v[80:81] op_sel_hi:[1,0]
	v_mov_b32_e32 v68, v65
	v_mul_f32_e32 v64, 0xbfb8aa3b, v73
	v_exp_f32_e32 v64, v64
	s_nop 0
	v_add_f32_e32 v64, 1.0, v64
	v_rcp_f32_e32 v64, v64
	s_nop 0
	v_mul_f32_e32 v64, v73, v64
	v_mul_f32_e32 v72, v72, v64
	v_pk_mul_f32 v[64:65], v[68:69], v[80:81] op_sel_hi:[1,0]
	s_nop 0
	v_mul_f32_e32 v68, 0xbfb8aa3b, v65
	v_exp_f32_e32 v68, v68
	s_nop 0
	v_add_f32_e32 v68, 1.0, v68
	v_rcp_f32_e32 v68, v68
	s_nop 0
	v_mul_f32_e32 v65, v65, v68
	v_mul_f32_e32 v68, v64, v65
	v_mov_b32_e32 v64, v66
	v_mov_b32_e32 v65, v70
	v_pk_mul_f32 v[64:65], v[64:65], v[80:81] op_sel_hi:[1,0]
	v_mov_b32_e32 v70, v67
	v_mul_f32_e32 v66, 0xbfb8aa3b, v65
	v_exp_f32_e32 v66, v66
	s_nop 0
	v_add_f32_e32 v66, 1.0, v66
	v_rcp_f32_e32 v66, v66
	s_nop 0
	v_mul_f32_e32 v65, v65, v66
	v_mul_f32_e32 v69, v64, v65
	v_pk_mul_f32 v[64:65], v[70:71], v[80:81] op_sel_hi:[1,0]
	v_add_u32_e32 v70, 48, v144
	v_mul_f32_e32 v66, 0xbfb8aa3b, v65
	v_exp_f32_e32 v66, v66
	s_nop 0
	v_add_f32_e32 v66, 1.0, v66
	v_rcp_f32_e32 v66, v66
	s_nop 0
	v_mul_f32_e32 v65, v65, v66
	v_mul_f32_e32 v67, v64, v65
	v_cvt_pk_bf16_f32 v64, v81, v76
	v_cvt_pk_bf16_f32 v65, v74, v75
	v_cvt_pk_bf16_f32 v66, v72, v68
	v_cvt_pk_bf16_f32 v67, v69, v67
	v_mad_i64_i32 v[68:69], s[4:5], v70, s3, v[112:113]
	v_lshl_add_u64 v[68:69], v[68:69], 0, s[0:1]
	v_lshl_add_u64 v[68:69], v[68:69], 0, s[34:35]
	v_lshl_add_u64 v[68:69], v[68:69], 0, v[184:185]
	global_store_dwordx4 v[68:69], v[64:67], off
	ds_read_b32 v64, v142 offset:512
	s_nop 0
	v_add_u32_e32 v65, 0x80, v144
	v_mov_b32_e32 v66, v56
	v_mov_b32_e32 v67, v60
	s_waitcnt lgkmcnt(0)
	v_pk_mul_f32 v[66:67], v[66:67], v[64:65] op_sel_hi:[1,0]
	v_mov_b32_e32 v60, v57
	v_mul_f32_e32 v56, 0xbfb8aa3b, v67
	v_exp_f32_e32 v56, v56
	s_nop 0
	v_add_f32_e32 v56, 1.0, v56
	v_rcp_f32_e32 v56, v56
	s_nop 0
	v_mul_f32_e32 v56, v67, v56
	v_mul_f32_e32 v66, v66, v56
	v_pk_mul_f32 v[56:57], v[60:61], v[64:65] op_sel_hi:[1,0]
	s_nop 0
	v_mul_f32_e32 v60, 0xbfb8aa3b, v57
	v_exp_f32_e32 v60, v60
	s_nop 0
	v_add_f32_e32 v60, 1.0, v60
	v_rcp_f32_e32 v60, v60
	s_nop 0
	v_mul_f32_e32 v57, v57, v60
	v_mul_f32_e32 v60, v56, v57
	v_mov_b32_e32 v56, v58
	v_mov_b32_e32 v57, v62
	v_pk_mul_f32 v[56:57], v[56:57], v[64:65] op_sel_hi:[1,0]
	v_mov_b32_e32 v62, v59
	v_mul_f32_e32 v58, 0xbfb8aa3b, v57
	v_exp_f32_e32 v58, v58
	s_nop 0
	v_add_f32_e32 v58, 1.0, v58
	v_rcp_f32_e32 v58, v58
	s_nop 0
	v_mul_f32_e32 v57, v57, v58
	v_mul_f32_e32 v58, v56, v57
	v_pk_mul_f32 v[56:57], v[62:63], v[64:65] op_sel_hi:[1,0]
	s_nop 0
	v_mul_f32_e32 v59, 0xbfb8aa3b, v57
	v_exp_f32_e32 v59, v59
	s_nop 0
	v_add_f32_e32 v59, 1.0, v59
	v_rcp_f32_e32 v59, v59
	s_nop 0
	v_mul_f32_e32 v57, v57, v59
	v_mul_f32_e32 v59, v56, v57
	v_mov_b32_e32 v56, v48
	v_mov_b32_e32 v57, v52
	v_pk_mul_f32 v[56:57], v[56:57], v[64:65] op_sel_hi:[1,0]
	v_mov_b32_e32 v52, v49
	v_mul_f32_e32 v48, 0xbfb8aa3b, v57
	v_exp_f32_e32 v48, v48
	s_nop 0
	v_add_f32_e32 v48, 1.0, v48
	v_rcp_f32_e32 v48, v48
	s_nop 0
	v_mul_f32_e32 v48, v57, v48
	v_mul_f32_e32 v56, v56, v48
	v_pk_mul_f32 v[48:49], v[52:53], v[64:65] op_sel_hi:[1,0]
	s_nop 0
	v_mul_f32_e32 v52, 0xbfb8aa3b, v49
	v_exp_f32_e32 v52, v52
	s_nop 0
	v_add_f32_e32 v52, 1.0, v52
	v_rcp_f32_e32 v52, v52
	s_nop 0
	v_mul_f32_e32 v49, v49, v52
	v_mul_f32_e32 v52, v48, v49
	v_mov_b32_e32 v48, v50
	v_mov_b32_e32 v49, v54
	v_pk_mul_f32 v[48:49], v[48:49], v[64:65] op_sel_hi:[1,0]
	v_mov_b32_e32 v54, v51
	v_mul_f32_e32 v50, 0xbfb8aa3b, v49
	v_exp_f32_e32 v50, v50
	s_nop 0
	v_add_f32_e32 v50, 1.0, v50
	v_rcp_f32_e32 v50, v50
	s_nop 0
	v_mul_f32_e32 v49, v49, v50
	v_mul_f32_e32 v53, v48, v49
	v_pk_mul_f32 v[48:49], v[54:55], v[64:65] op_sel_hi:[1,0]
	s_nop 0
	v_mul_f32_e32 v50, 0xbfb8aa3b, v49
	v_exp_f32_e32 v50, v50
	s_nop 0
	v_add_f32_e32 v50, 1.0, v50
	v_rcp_f32_e32 v50, v50
	s_nop 0
	v_mul_f32_e32 v49, v49, v50
	v_mul_f32_e32 v51, v48, v49
	v_cvt_pk_bf16_f32 v48, v66, v60
	v_cvt_pk_bf16_f32 v49, v58, v59
	v_cvt_pk_bf16_f32 v50, v56, v52
	v_cvt_pk_bf16_f32 v51, v53, v51
	v_mad_i64_i32 v[52:53], s[4:5], v65, s3, v[112:113]
	v_lshl_add_u64 v[52:53], v[52:53], 0, s[0:1]
	v_lshl_add_u64 v[52:53], v[52:53], 0, s[34:35]
	v_lshl_add_u64 v[52:53], v[52:53], 0, v[184:185]
	global_store_dwordx4 v[52:53], v[48:51], off
	ds_read_b32 v48, v142 offset:576
	s_nop 0
	v_mov_b32_e32 v50, v40
	v_mov_b32_e32 v51, v44
	v_mov_b32_e32 v44, v41
	s_waitcnt lgkmcnt(0)
; __device__ __forceinline__ u32x4 pack8(const f32x4 a, const f32x4 b) { u32x4 w; w.x = cvt_pk_bf16(a[0], a[1]); w.y = cvt_pk_bf16(a[2], a[3]); w.z = cvt_pk_bf16(b[0], b[1]); w.w = cvt_pk_bf16(b[2], b[3]); return w; }
;     __device__ __forceinline__ void operator()(const f32x4 (&acc)[2][2][4][2], const Unit& u, int wr, int wc, int fr, int fq) const {
;     ...
;         for (int ai = 0; ai < 2; ++ai)
; #pragma unroll
;             for (int m = 0; m < 4; ++m) {
;                 const int row = u.pm * BM + ai * HALF + wr * 64 + m * 16 + fr;
;                 const float rs = R[ai * HALF + wr * 64 + m * 16 + fr];
;                 bf16_t* ACT = (bf16_t*)(ws + WS_ACT);
;                 f32x4 a[2];
; #pragma unroll
;                 for (int n = 0; n < 2; ++n) {
;                     const f32x4 g = acc[ai][0][m][n] * rs, uu = acc[ai][1][m][n] * rs;
; #pragma unroll
;                     for (int j = 0; j < 4; ++j) a[n][j] = g[j] * __builtin_amdgcn_rcpf(1.0f + __builtin_amdgcn_exp2f(-1.4426950408889634f * g[j])) * uu[j];
;                 }
;                 *(u32x4*)(ACT + (size_t)row * 2816 + u.pn * 128 + wc * 32 + 8 * fq) = pack8(a[0], a[1]);
;             }
	v_pk_mul_f32 v[50:51], v[50:51], v[48:49] op_sel_hi:[1,0]
	s_nop 0
	v_mul_f32_e32 v40, 0xbfb8aa3b, v51
	v_exp_f32_e32 v40, v40
	s_nop 0
	v_add_f32_e32 v40, 1.0, v40
	v_rcp_f32_e32 v40, v40
	s_nop 0
	v_mul_f32_e32 v40, v51, v40
	v_mul_f32_e32 v49, v50, v40
	v_pk_mul_f32 v[40:41], v[44:45], v[48:49] op_sel_hi:[1,0]
	s_nop 0
	v_mul_f32_e32 v44, 0xbfb8aa3b, v41
	v_exp_f32_e32 v44, v44
	s_nop 0
	v_add_f32_e32 v44, 1.0, v44
	v_rcp_f32_e32 v44, v44
	s_nop 0
	v_mul_f32_e32 v41, v41, v44
	v_mul_f32_e32 v44, v40, v41
	v_mov_b32_e32 v40, v42
	v_mov_b32_e32 v41, v46
	v_pk_mul_f32 v[40:41], v[40:41], v[48:49] op_sel_hi:[1,0]
	v_mov_b32_e32 v46, v43
	v_mul_f32_e32 v42, 0xbfb8aa3b, v41
	v_exp_f32_e32 v42, v42
	s_nop 0
	v_add_f32_e32 v42, 1.0, v42
	v_rcp_f32_e32 v42, v42
	s_nop 0
	v_mul_f32_e32 v41, v41, v42
	v_mul_f32_e32 v42, v40, v41
	v_pk_mul_f32 v[40:41], v[46:47], v[48:49] op_sel_hi:[1,0]
	s_nop 0
	v_mul_f32_e32 v43, 0xbfb8aa3b, v41
	v_exp_f32_e32 v43, v43
	s_nop 0
	v_add_f32_e32 v43, 1.0, v43
	v_rcp_f32_e32 v43, v43
	s_nop 0
	v_mul_f32_e32 v41, v41, v43
	v_mul_f32_e32 v43, v40, v41
	v_mov_b32_e32 v40, v32
	v_mov_b32_e32 v41, v36
	v_pk_mul_f32 v[40:41], v[40:41], v[48:49] op_sel_hi:[1,0]
	v_mov_b32_e32 v36, v33
	v_mul_f32_e32 v32, 0xbfb8aa3b, v41
	v_exp_f32_e32 v32, v32
	s_nop 0
	v_add_f32_e32 v32, 1.0, v32
	v_rcp_f32_e32 v32, v32
	s_nop 0
	v_mul_f32_e32 v32, v41, v32
	v_mul_f32_e32 v40, v40, v32
	v_pk_mul_f32 v[32:33], v[36:37], v[48:49] op_sel_hi:[1,0]
	s_nop 0
	v_mul_f32_e32 v36, 0xbfb8aa3b, v33
	v_exp_f32_e32 v36, v36
	s_nop 0
	v_add_f32_e32 v36, 1.0, v36
	v_rcp_f32_e32 v36, v36
	s_nop 0
	v_mul_f32_e32 v33, v33, v36
	v_mul_f32_e32 v36, v32, v33
	v_mov_b32_e32 v32, v34
	v_mov_b32_e32 v33, v38
	v_pk_mul_f32 v[32:33], v[32:33], v[48:49] op_sel_hi:[1,0]
	v_mov_b32_e32 v38, v35
	v_mul_f32_e32 v34, 0xbfb8aa3b, v33
	v_exp_f32_e32 v34, v34
	s_nop 0
	v_add_f32_e32 v34, 1.0, v34
	v_rcp_f32_e32 v34, v34
	s_nop 0
	v_mul_f32_e32 v33, v33, v34
	v_mul_f32_e32 v37, v32, v33
	v_pk_mul_f32 v[32:33], v[38:39], v[48:49] op_sel_hi:[1,0]
	v_add_u32_e32 v38, 0x90, v144
	v_mul_f32_e32 v34, 0xbfb8aa3b, v33
	v_exp_f32_e32 v34, v34
	s_nop 0
	v_add_f32_e32 v34, 1.0, v34
	v_rcp_f32_e32 v34, v34
	s_nop 0
	v_mul_f32_e32 v33, v33, v34
	v_mul_f32_e32 v35, v32, v33
	v_cvt_pk_bf16_f32 v32, v49, v44
	v_cvt_pk_bf16_f32 v33, v42, v43
	v_cvt_pk_bf16_f32 v34, v40, v36
	v_cvt_pk_bf16_f32 v35, v37, v35
	v_mad_i64_i32 v[36:37], s[4:5], v38, s3, v[112:113]
	v_lshl_add_u64 v[36:37], v[36:37], 0, s[0:1]
	v_lshl_add_u64 v[36:37], v[36:37], 0, s[34:35]
	v_lshl_add_u64 v[36:37], v[36:37], 0, v[184:185]
	global_store_dwordx4 v[36:37], v[32:35], off
	ds_read_b32 v32, v142 offset:640
	s_nop 0
	v_mov_b32_e32 v34, v24
	v_mov_b32_e32 v35, v28
	v_mov_b32_e32 v28, v25
	s_waitcnt lgkmcnt(0)
; __device__ __forceinline__ u32x4 pack8(const f32x4 a, const f32x4 b) { u32x4 w; w.x = cvt_pk_bf16(a[0], a[1]); w.y = cvt_pk_bf16(a[2], a[3]); w.z = cvt_pk_bf16(b[0], b[1]); w.w = cvt_pk_bf16(b[2], b[3]); return w; }
;     __device__ __forceinline__ void operator()(const f32x4 (&acc)[2][2][4][2], const Unit& u, int wr, int wc, int fr, int fq) const {
;     ...
;         for (int ai = 0; ai < 2; ++ai)
; #pragma unroll
;             for (int m = 0; m < 4; ++m) {
;                 const int row = u.pm * BM + ai * HALF + wr * 64 + m * 16 + fr;
;                 const float rs = R[ai * HALF + wr * 64 + m * 16 + fr];
;                 bf16_t* ACT = (bf16_t*)(ws + WS_ACT);
;                 f32x4 a[2];
; #pragma unroll
;                 for (int n = 0; n < 2; ++n) {
;                     const f32x4 g = acc[ai][0][m][n] * rs, uu = acc[ai][1][m][n] * rs;
; #pragma unroll
;                     for (int j = 0; j < 4; ++j) a[n][j] = g[j] * __builtin_amdgcn_rcpf(1.0f + __builtin_amdgcn_exp2f(-1.4426950408889634f * g[j])) * uu[j];
;                 }
;                 *(u32x4*)(ACT + (size_t)row * 2816 + u.pn * 128 + wc * 32 + 8 * fq) = pack8(a[0], a[1]);
;             }
	v_pk_mul_f32 v[34:35], v[34:35], v[32:33] op_sel_hi:[1,0]
	s_nop 0
	v_mul_f32_e32 v24, 0xbfb8aa3b, v35
	v_exp_f32_e32 v24, v24
	s_nop 0
	v_add_f32_e32 v24, 1.0, v24
	v_rcp_f32_e32 v24, v24
	s_nop 0
	v_mul_f32_e32 v24, v35, v24
	v_mul_f32_e32 v33, v34, v24
	v_pk_mul_f32 v[24:25], v[28:29], v[32:33] op_sel_hi:[1,0]
	s_nop 0
	v_mul_f32_e32 v28, 0xbfb8aa3b, v25
	v_exp_f32_e32 v28, v28
	s_nop 0
	v_add_f32_e32 v28, 1.0, v28
	v_rcp_f32_e32 v28, v28
	s_nop 0
	v_mul_f32_e32 v25, v25, v28
	v_mul_f32_e32 v28, v24, v25
	v_mov_b32_e32 v24, v26
	v_mov_b32_e32 v25, v30
	v_pk_mul_f32 v[24:25], v[24:25], v[32:33] op_sel_hi:[1,0]
	v_mov_b32_e32 v30, v27
	v_mul_f32_e32 v26, 0xbfb8aa3b, v25
	v_exp_f32_e32 v26, v26
	s_nop 0
	v_add_f32_e32 v26, 1.0, v26
	v_rcp_f32_e32 v26, v26
	s_nop 0
	v_mul_f32_e32 v25, v25, v26
	v_mul_f32_e32 v26, v24, v25
	v_pk_mul_f32 v[24:25], v[30:31], v[32:33] op_sel_hi:[1,0]
	s_nop 0
	v_mul_f32_e32 v27, 0xbfb8aa3b, v25
	v_exp_f32_e32 v27, v27
	s_nop 0
	v_add_f32_e32 v27, 1.0, v27
	v_rcp_f32_e32 v27, v27
	s_nop 0
	v_mul_f32_e32 v25, v25, v27
	v_mul_f32_e32 v27, v24, v25
	v_mov_b32_e32 v24, v16
	v_mov_b32_e32 v25, v20
	v_pk_mul_f32 v[24:25], v[24:25], v[32:33] op_sel_hi:[1,0]
	v_mov_b32_e32 v20, v17
	v_mul_f32_e32 v16, 0xbfb8aa3b, v25
	v_exp_f32_e32 v16, v16
	s_nop 0
	v_add_f32_e32 v16, 1.0, v16
	v_rcp_f32_e32 v16, v16
	s_nop 0
	v_mul_f32_e32 v16, v25, v16
	v_mul_f32_e32 v24, v24, v16
	v_pk_mul_f32 v[16:17], v[20:21], v[32:33] op_sel_hi:[1,0]
	s_nop 0
	v_mul_f32_e32 v20, 0xbfb8aa3b, v17
	v_exp_f32_e32 v20, v20
	s_nop 0
	v_add_f32_e32 v20, 1.0, v20
	v_rcp_f32_e32 v20, v20
	s_nop 0
	v_mul_f32_e32 v17, v17, v20
	v_mul_f32_e32 v20, v16, v17
	v_mov_b32_e32 v16, v18
	v_mov_b32_e32 v17, v22
	v_pk_mul_f32 v[16:17], v[16:17], v[32:33] op_sel_hi:[1,0]
	v_mov_b32_e32 v22, v19
	v_mul_f32_e32 v18, 0xbfb8aa3b, v17
	v_exp_f32_e32 v18, v18
	s_nop 0
	v_add_f32_e32 v18, 1.0, v18
	v_rcp_f32_e32 v18, v18
	s_nop 0
	v_mul_f32_e32 v17, v17, v18
	v_mul_f32_e32 v21, v16, v17
	v_pk_mul_f32 v[16:17], v[22:23], v[32:33] op_sel_hi:[1,0]
	v_add_u32_e32 v22, 0xa0, v144
	v_mul_f32_e32 v18, 0xbfb8aa3b, v17
	v_exp_f32_e32 v18, v18
	s_nop 0
	v_add_f32_e32 v18, 1.0, v18
	v_rcp_f32_e32 v18, v18
	s_nop 0
	v_mul_f32_e32 v17, v17, v18
	v_mul_f32_e32 v19, v16, v17
	v_cvt_pk_bf16_f32 v16, v33, v28
	v_cvt_pk_bf16_f32 v17, v26, v27
	v_cvt_pk_bf16_f32 v18, v24, v20
	v_cvt_pk_bf16_f32 v19, v21, v19
	v_mad_i64_i32 v[20:21], s[4:5], v22, s3, v[112:113]
	v_lshl_add_u64 v[20:21], v[20:21], 0, s[0:1]
	v_lshl_add_u64 v[20:21], v[20:21], 0, s[34:35]
	v_lshl_add_u64 v[20:21], v[20:21], 0, v[184:185]
	global_store_dwordx4 v[20:21], v[16:19], off
	ds_read_b32 v16, v142 offset:704
	s_nop 0
	v_mov_b32_e32 v18, v8
	v_mov_b32_e32 v19, v12
	v_mov_b32_e32 v12, v9
	s_waitcnt lgkmcnt(0)
	v_pk_mul_f32 v[18:19], v[18:19], v[16:17] op_sel_hi:[1,0]
	s_nop 0
	v_mul_f32_e32 v8, 0xbfb8aa3b, v19
	v_exp_f32_e32 v8, v8
	s_nop 0
	v_add_f32_e32 v8, 1.0, v8
	v_rcp_f32_e32 v8, v8
	s_nop 0
	v_mul_f32_e32 v8, v19, v8
	v_mul_f32_e32 v17, v18, v8
	v_pk_mul_f32 v[8:9], v[12:13], v[16:17] op_sel_hi:[1,0]
	s_nop 0
	v_mul_f32_e32 v12, 0xbfb8aa3b, v9
	v_exp_f32_e32 v12, v12
	s_nop 0
	v_add_f32_e32 v12, 1.0, v12
	v_rcp_f32_e32 v12, v12
	s_nop 0
	v_mul_f32_e32 v9, v9, v12
	v_mul_f32_e32 v12, v8, v9
	v_mov_b32_e32 v8, v10
	v_mov_b32_e32 v9, v14
	v_pk_mul_f32 v[8:9], v[8:9], v[16:17] op_sel_hi:[1,0]
	v_mov_b32_e32 v14, v11
	v_mul_f32_e32 v10, 0xbfb8aa3b, v9
	v_exp_f32_e32 v10, v10
	s_nop 0
	v_add_f32_e32 v10, 1.0, v10
	v_rcp_f32_e32 v10, v10
	s_nop 0
	v_mul_f32_e32 v9, v9, v10
	v_mul_f32_e32 v10, v8, v9
	v_pk_mul_f32 v[8:9], v[14:15], v[16:17] op_sel_hi:[1,0]
	s_nop 0
	v_mul_f32_e32 v11, 0xbfb8aa3b, v9
	v_exp_f32_e32 v11, v11
	s_nop 0
	v_add_f32_e32 v11, 1.0, v11
	v_rcp_f32_e32 v11, v11
	s_nop 0
	v_mul_f32_e32 v9, v9, v11
	v_mul_f32_e32 v11, v8, v9
	v_mov_b32_e32 v8, v0
	v_mov_b32_e32 v9, v4
	v_pk_mul_f32 v[8:9], v[8:9], v[16:17] op_sel_hi:[1,0]
	v_mov_b32_e32 v4, v1
	v_mul_f32_e32 v0, 0xbfb8aa3b, v9
	v_exp_f32_e32 v0, v0
	s_nop 0
	v_add_f32_e32 v0, 1.0, v0
	v_rcp_f32_e32 v0, v0
	s_nop 0
	v_mul_f32_e32 v0, v9, v0
	v_mul_f32_e32 v8, v8, v0
	v_pk_mul_f32 v[0:1], v[4:5], v[16:17] op_sel_hi:[1,0]
	s_nop 0
	v_mul_f32_e32 v4, 0xbfb8aa3b, v1
	v_exp_f32_e32 v4, v4
	s_nop 0
	v_add_f32_e32 v4, 1.0, v4
	v_rcp_f32_e32 v4, v4
	s_nop 0
	v_mul_f32_e32 v1, v1, v4
	v_mul_f32_e32 v4, v0, v1
	v_mov_b32_e32 v0, v2
	v_mov_b32_e32 v1, v6
	v_pk_mul_f32 v[0:1], v[0:1], v[16:17] op_sel_hi:[1,0]
	v_mov_b32_e32 v6, v3
	v_mul_f32_e32 v2, 0xbfb8aa3b, v1
	v_exp_f32_e32 v2, v2
	s_nop 0
	v_add_f32_e32 v2, 1.0, v2
	v_rcp_f32_e32 v2, v2
	s_nop 0
	v_mul_f32_e32 v1, v1, v2
	v_mul_f32_e32 v5, v0, v1
	v_pk_mul_f32 v[0:1], v[6:7], v[16:17] op_sel_hi:[1,0]
	v_add_u32_e32 v6, 0xb0, v144
	v_mul_f32_e32 v2, 0xbfb8aa3b, v1
	v_exp_f32_e32 v2, v2
	s_nop 0
	v_add_f32_e32 v2, 1.0, v2
	v_rcp_f32_e32 v2, v2
	s_nop 0
	v_mul_f32_e32 v1, v1, v2
	v_mul_f32_e32 v3, v0, v1
	v_cvt_pk_bf16_f32 v0, v17, v12
	v_cvt_pk_bf16_f32 v1, v10, v11
	v_cvt_pk_bf16_f32 v2, v8, v4
	v_cvt_pk_bf16_f32 v3, v5, v3
	v_mad_i64_i32 v[4:5], s[4:5], v6, s3, v[112:113]
	v_lshl_add_u64 v[4:5], v[4:5], 0, s[0:1]
	v_lshl_add_u64 v[4:5], v[4:5], 0, s[34:35]
	v_lshl_add_u64 v[4:5], v[4:5], 0, v[184:185]
	s_mov_b64 s[0:1], -1
	global_store_dwordx4 v[4:5], v[0:3], off
	s_cbranch_vccnz .LBB0_31
	s_andn2_b64 vcc, exec, s[8:9]
	s_cbranch_vccnz .LBB0_30
	s_barrier
	s_branch .LBB0_30

; #define LAS __attribute__((address_space(3)))
; #define LAS __attribute__((address_space(3)))
; __global__ void __launch_bounds__(NWAVES * 64, 2) hymba_fwd(Args args) {
;     ...
;                 if (l + 1 < DEPTH && blockIdx.x >= 48) {
;                     int ln = lane, tn = tid; asm volatile("" : "+v"(ln), "+v"(tn));
;                     const int wk = ((int)blockIdx.x - 48) * NWAVES + wave, nwk = (G - 48) * NWAVES;
;                     convert_layer_weights(args, ws, (LAS float*)(lds + wave * 16384), l + 1, wk, nwk, ln, 12);
;                     convert_layer_caches(args, ws, (LAS float*)(lds + wave * 16384), l + 1, wk, nwk, ((int)blockIdx.x - 48) * (NWAVES * 64) + tn, (G - 48) * NWAVES * 64, ln);
;                 }
.LBB0_46:
	v_readlane_b32 s98, v251, 0
	s_nop 0
	s_cmp_ge_u32 s98, 0xb0
	s_cbranch_scc1 .LBB0_204
	s_cmp_gt_i32 s54, 15
	v_readlane_b32 s2, v255, 5
	s_cselect_b64 s[0:1], -1, 0
	v_readlane_b32 s3, v255, 6
	s_or_b64 s[0:1], s[2:3], s[0:1]
	s_and_b64 vcc, exec, s[0:1]
	s_cbranch_vccnz .LBB0_204
	v_readlane_b32 s0, v255, 19
	v_readlane_b32 s1, v255, 20
	s_add_i32 s4, s0, 1
	v_readlane_b32 s0, v251, 9
	v_and_b32_e32 v55, 63, v216
	v_mov_b32_e32 v1, v216
	v_readlane_b32 s1, v251, 10
	s_andn2_b64 vcc, exec, s[0:1]
	v_ashrrev_i32_e32 v18, 5, v55
	v_ashrrev_i32_e32 v19, 3, v55
	v_lshlrev_b32_e32 v0, 3, v55
	s_movk_i32 s0, 0x84
	v_mul_lo_u32 v20, v18, s0
	v_add_u32_e32 v21, 2, v18
	v_add_u32_e32 v22, 4, v18
	v_add_u32_e32 v23, 6, v18
	v_add_u32_e32 v24, 8, v18
	v_add_u32_e32 v25, 10, v18
	v_add_u32_e32 v26, 12, v18
	v_add_u32_e32 v27, 14, v18
	v_add_u32_e32 v28, 16, v18
	v_add_u32_e32 v29, 18, v18
	v_add_u32_e32 v30, 20, v18
	v_add_u32_e32 v31, 22, v18
	v_add_u32_e32 v32, 24, v18
	v_add_u32_e32 v33, 26, v18
	v_add_u32_e32 v34, 28, v18
	v_add_u32_e32 v35, 30, v18
	v_add_u32_e32 v36, 32, v18
	v_add_u32_e32 v37, 34, v18
	v_add_u32_e32 v38, 36, v18
	v_add_u32_e32 v39, 38, v18
	v_add_u32_e32 v40, 40, v18
	v_add_u32_e32 v41, 42, v18
	v_add_u32_e32 v42, 44, v18
	v_add_u32_e32 v43, 46, v18
	v_add_u32_e32 v44, 48, v18
	v_add_u32_e32 v45, 50, v18
	v_add_u32_e32 v46, 52, v18
	v_add_u32_e32 v47, 54, v18
	v_add_u32_e32 v48, 56, v18
	v_add_u32_e32 v49, 58, v18
	v_add_u32_e32 v50, 60, v18
	v_add_u32_e32 v51, 62, v18
	v_and_b32_e32 v0, 56, v0
	v_lshlrev_b32_e32 v56, 2, v19
	v_add_u32_e32 v52, 8, v19
	v_add_u32_e32 v53, 16, v19
	v_add_u32_e32 v54, 24, v19
	v_readlane_b32 s6, v251, 14
	s_cbranch_vccnz .LBB0_191
	s_lshl_b32 s100, s4, 8
	s_or_b32 s100, s100, 0x530000c
	s_mov_b32 s101, 1
	s_branch .Lcvt_entry
.Lcvt_ret1:
.LBB0_191:
	v_readlane_b32 s0, v251, 15
	v_readlane_b32 s1, v251, 16
	s_andn2_b64 vcc, exec, s[0:1]
	s_mul_i32 s5, s4, 40
	s_cbranch_vccnz .LBB0_198
	s_lshl_b32 s100, s4, 8
	s_or_b32 s100, s100, 0x5300060
	s_mov_b32 s101, 2
	s_branch .Lcvt_entry

; #define LAS __attribute__((address_space(3)))
; #define LAS __attribute__((address_space(3)))
; __device__ __forceinline__ void convert_layer_weights(const Args& a, unsigned char* ws, LAS float* scr, int l, int gw, int NGW, int lane, int which) {
;     constexpr int C_IN = 896, C_OUT = 512, C_GU = 2816, C_DN = 1408;
;     const int n_in = (which & 1) ? C_IN : 0, n_out = (which & 2) ? C_OUT : 0, n_gu = (which & 4) ? C_GU : 0, n_dn = (which & 8) ? C_DN : 0;
;     for (int it = gw; it < n_in + n_out + n_gu + n_dn; it += NGW) {
;         int r = it;
;         if (r < n_in) { const int kb = r / 56, nb = r % 56; p0_transpose_item(a.in[9] + (size_t)l * D * INW, INW, D, a.in[8] + l * D, (bf16*)(ws + WS_WIN) + (size_t)l * INW * D, perm_in(32 * nb), 32 * nb, 64 * kb, scr, lane); continue; } r -= n_in;
.Lcvt_entry:
	v_writelane_b32 v183, s0, 0
	v_writelane_b32 v183, s1, 1
	v_writelane_b32 v183, s2, 2
	v_writelane_b32 v183, s3, 3
	v_writelane_b32 v183, s4, 4
	v_writelane_b32 v183, s5, 5
	v_writelane_b32 v183, s6, 6
	v_writelane_b32 v183, s7, 7
	v_writelane_b32 v183, s8, 8
	v_writelane_b32 v183, s9, 9
	v_writelane_b32 v183, s10, 10
	v_writelane_b32 v183, s11, 11
	v_writelane_b32 v183, s12, 12
	v_writelane_b32 v183, s13, 13
	v_writelane_b32 v183, s14, 14
	v_writelane_b32 v183, s15, 15
	v_writelane_b32 v183, s16, 16
	v_writelane_b32 v183, s17, 17
	v_writelane_b32 v183, s18, 18
	v_writelane_b32 v183, s19, 19
	v_writelane_b32 v183, s20, 20
	v_writelane_b32 v183, s21, 21
	v_writelane_b32 v183, s22, 22
	v_writelane_b32 v183, s23, 23
	v_writelane_b32 v183, s24, 24
	v_writelane_b32 v183, s25, 25
	v_writelane_b32 v183, s26, 26
	v_writelane_b32 v183, s27, 27
	v_writelane_b32 v183, s28, 28
	v_writelane_b32 v183, s29, 29
	v_writelane_b32 v183, s30, 30
	v_writelane_b32 v183, s31, 31
	v_writelane_b32 v183, s32, 32
	v_writelane_b32 v183, s33, 33
	v_writelane_b32 v183, s34, 34
	v_writelane_b32 v183, s35, 35
	v_writelane_b32 v183, s36, 36
	v_writelane_b32 v183, s37, 37
	v_writelane_b32 v183, s38, 38
	v_writelane_b32 v183, s39, 39
	v_writelane_b32 v183, s40, 40
	v_writelane_b32 v183, s41, 41
	v_writelane_b32 v183, s42, 42
	v_writelane_b32 v183, s43, 43
	v_writelane_b32 v183, s44, 44
	v_writelane_b32 v183, s45, 45
	v_writelane_b32 v183, s46, 46
	v_writelane_b32 v183, s47, 47
	v_writelane_b32 v183, s48, 48
	v_writelane_b32 v183, s49, 49
	v_writelane_b32 v183, s50, 50
	v_writelane_b32 v183, s51, 51
	v_writelane_b32 v183, s52, 52
	v_writelane_b32 v183, s53, 53
	v_writelane_b32 v183, s54, 54
	v_writelane_b32 v183, s55, 55
	v_writelane_b32 v183, s56, 56
	v_writelane_b32 v183, s57, 57
	v_writelane_b32 v183, s58, 58
	v_writelane_b32 v183, s59, 59
	v_writelane_b32 v183, s60, 60
	v_writelane_b32 v183, s61, 61
	v_writelane_b32 v183, s62, 62
	v_writelane_b32 v183, s63, 63
	v_writelane_b32 v182, s64, 0
	v_writelane_b32 v182, s65, 1
	v_writelane_b32 v182, s66, 2
	v_writelane_b32 v182, s67, 3
	s_mov_b64 s[64:65], exec
	v_writelane_b32 v182, s64, 4
	v_writelane_b32 v182, s65, 5
	s_mov_b64 exec, -1
	v_readlane_b32 s0, v251, 3
	v_readlane_b32 s1, v251, 4
	s_sub_u32 s0, s0, 0xd0
	s_subb_u32 s1, s1, 0
	s_load_dwordx2 s[2:3], s[0:1], 0xc0
	s_load_dword s20, s[0:1], 0xd0
	s_load_dwordx2 s[36:37], s[0:1], 0x20
	s_load_dwordx2 s[38:39], s[0:1], 0x38
	s_load_dwordx4 s[40:43], s[0:1], 0x40
	s_load_dwordx4 s[44:47], s[0:1], 0x70
	s_load_dwordx4 s[48:51], s[0:1], 0x90
	s_load_dwordx4 s[52:55], s[0:1], 0xa0
	s_load_dwordx2 s[56:57], s[0:1], 0xb0
	v_readlane_b32 s21, v251, 0
	v_readfirstlane_b32 s22, v216
	s_lshr_b32 s22, s22, 6
	s_bfe_u32 s23, s100, 0x80010
	s_bfe_u32 s7, s100, 0x80008
	v_and_b32_e32 v180, 31, v216
	v_bfe_u32 v179, v216, 5, 1
	v_lshlrev_b32_e32 v177, 7, v179
	s_waitcnt lgkmcnt(0)
	s_sub_i32 s21, s21, s23
	s_sub_i32 s20, s20, s23
	s_lshr_b32 s16, s100, 24
	s_lshl_b32 s16, s16, 4
	s_sub_i32 s20, s20, s16
	s_lshl_b32 s4, s21, 3
	s_add_i32 s4, s4, s22
	s_lshl_b32 s5, s20, 3
	s_bitcmp1_b32 s100, 0
	s_cselect_b32 s60, 0x380, 0
	s_bitcmp1_b32 s100, 1
	s_cselect_b32 s16, 0x200, 0
	s_add_i32 s61, s60, s16
	s_bitcmp1_b32 s100, 2
	s_cselect_b32 s16, 0xb00, 0
	s_add_i32 s62, s61, s16
	s_bitcmp1_b32 s100, 3
	s_cselect_b32 s16, 0x580, 0
	s_add_i32 s63, s62, s16
	s_bitcmp1_b32 s100, 4
	s_cselect_b32 s16, 0x400, 0
	s_add_i32 s64, s63, s16
	s_bitcmp1_b32 s100, 5
	s_cselect_b32 s16, 0x400, 0
	s_add_i32 s65, s64, s16
	s_bitcmp1_b32 s100, 6
	s_cselect_b32 s16, 0x100, 0
	s_add_i32 s66, s65, s16
